# RWKV producer waves: v_sqrt_f32 / v_rcp_f32 in the key normalisation instead of the IEEE expansions
# speedup vs baseline: 1.0056x; 1.0056x over previous
; #define LAS __attribute__((address_space(3)))
; __device__ __forceinline__ f32x4 unpack4(u32x2 u) { return (f32x4){__uint_as_float(u.x << 16), __uint_as_float(u.x & 0xffff0000u), __uint_as_float(u.y << 16), __uint_as_float(u.y & 0xffff0000u)}; }
; __device__ __forceinline__ float dot4(f32x4 a, f32x4 b) { return (a.x * b.x + a.y * b.y) + (a.z * b.z + a.w * b.w); }
; template <int ph>
; __device__ __forceinline__ void run_phase(const Args& args, LAS unsigned char* lds, const int G, const int bx, const bool fin = true) {
;     ...
;             auto derive = [&](int buf) {
;                 LAS float* V = VECb + buf * VB;
; #pragma unroll
;                 for (int it = 0; it < 2; ++it) {
;                     const int tt = tt0 + 16 * it;
;                     const f32x4 pr = unpack4(q_r[it]), pk = unpack4(q_k[it]), pv = unpack4(q_v[it]);
;                     const f32x4 r = pr + (unpack4(q_rp[it]) - pr) * mu_r, k = pk + (unpack4(q_kp[it]) - pk) * mu_k, v = pv + (unpack4(q_vp[it]) - pv) * mu_v;
;                     const f32x4 e = unpack4(q_e[it]), a = unpack4(q_a[it]);
;                     const f32x4 w = (f32x4){__expf(-e[0]), __expf(-e[1]), __expf(-e[2]), __expf(-e[3])};
;                     f32x4 kk = k * kkc; const float n2 = red16(dot4(kk, kk)); kk = kk * (1.0f / fmaxf(sqrtf(n2), 1e-12f));
;                     const f32x4 kp = k * (1.0f + (a - 1.0f) * kac), bv = kk * a, wrv = w * r;
;                     const float br = red16(dot4(bv, r)), kr = red16(dot4(kp, r));
;                     const int o = tt * 64 + 4 * cgq;
;                     *(LAS f32x4*)(V + 0 * TC * 64 + o) = -kk; *(LAS f32x4*)(V + 1 * TC * 64 + o) = wrv; *(LAS f32x4*)(V + 2 * TC * 64 + o) = w;
;                     *(LAS f32x4*)(V + 3 * TC * 64 + o) = bv; *(LAS f32x4*)(V + 4 * TC * 64 + o) = kp; *(LAS f32x4*)(V + 5 * TC * 64 + o) = v;
;                     if (cgq == 0) *(LAS f32x2*)(SCb + buf * TC * 2 + 2 * tt) = (f32x2){br, kr};
;                 }
;             };
.LBB0_999:
	s_or_b64 exec, exec, s[0:1]
	v_lshlrev_b64 v[34:35], 11, v[34:35]
	v_lshl_add_u64 v[36:37], s[20:21], 0, v[34:35]
	v_lshl_add_u64 v[36:37], v[36:37], 0, v[20:21]
	global_load_dwordx2 v[38:39], v[36:37], off
	v_lshl_add_u64 v[34:35], s[22:23], 0, v[34:35]
	v_lshl_add_u64 v[34:35], v[34:35], 0, v[20:21]
	global_load_dwordx2 v[40:41], v[34:35], off
	v_or_b32_e32 v34, s42, v74
	v_mov_b64_e32 v[36:37], s[8:9]
	v_mov_b32_e32 v35, s43
	s_waitcnt vmcnt(0)
	v_lshlrev_b32_e32 v42, 16, v30
	v_and_b32_e32 v43, 0xffff0000, v30
	v_lshlrev_b32_e32 v44, 16, v26
	v_and_b32_e32 v45, 0xffff0000, v26
	v_lshlrev_b32_e32 v26, 16, v27
	v_and_b32_e32 v27, 0xffff0000, v27
	v_lshlrev_b32_e32 v46, 16, v28
	v_and_b32_e32 v47, 0xffff0000, v28
	v_lshlrev_b32_e32 v28, 16, v29
	v_and_b32_e32 v29, 0xffff0000, v29
	v_lshlrev_b32_e32 v48, 16, v32
	v_and_b32_e32 v49, 0xffff0000, v32
	v_lshlrev_b32_e32 v50, 16, v24
	v_and_b32_e32 v51, 0xffff0000, v24
	v_lshlrev_b32_e32 v52, 16, v25
	v_and_b32_e32 v53, 0xffff0000, v25
	v_lshlrev_b32_e32 v54, 16, v22
	v_and_b32_e32 v55, 0xffff0000, v22
	v_lshlrev_b32_e32 v56, 16, v23
	v_and_b32_e32 v57, 0xffff0000, v23
	v_mad_u64_u32 v[22:23], s[0:1], v34, s52, v[36:37]
	v_lshlrev_b32_e32 v30, 16, v31
	v_and_b32_e32 v31, 0xffff0000, v31
	v_lshlrev_b32_e32 v32, 16, v33
	v_and_b32_e32 v33, 0xffff0000, v33
	v_lshlrev_b64 v[24:25], 11, v[34:35]
	v_sub_f32_e32 v35, v49, v43
	v_sub_f32_e32 v34, v48, v42
	v_sub_f32_e32 v37, v51, v45
	v_sub_f32_e32 v36, v50, v44
	v_sub_f32_e32 v49, v53, v27
	v_sub_f32_e32 v48, v52, v26
	v_sub_f32_e32 v53, v57, v29
	v_sub_f32_e32 v52, v56, v28
	v_mad_i32_i24 v23, s43, v153, v23
	v_sub_f32_e32 v33, v33, v31
	v_sub_f32_e32 v32, v32, v30
	v_pk_fma_f32 v[58:59], v[12:13], v[36:37], v[44:45]
	v_pk_fma_f32 v[44:45], v[10:11], v[52:53], v[28:29]
	v_lshl_add_u64 v[28:29], v[22:23], 0, v[20:21]
	v_pk_fma_f32 v[88:89], v[18:19], v[32:33], v[30:31]
	v_add_co_u32_e32 v32, vcc, s53, v28
	v_sub_f32_e32 v51, v55, v47
	v_sub_f32_e32 v50, v54, v46
	v_lshl_add_u64 v[54:55], s[20:21], 0, v[24:25]
	v_lshl_add_u64 v[24:25], s[22:23], 0, v[24:25]
	v_addc_co_u32_e32 v33, vcc, 0, v29, vcc
	v_pk_fma_f32 v[66:67], v[16:17], v[34:35], v[42:43]
	v_pk_fma_f32 v[42:43], v[8:9], v[50:51], v[46:47]
	v_lshl_add_u64 v[22:23], v[54:55], 0, v[20:21]
	v_lshl_add_u64 v[30:31], v[24:25], 0, v[20:21]
	v_add_co_u32_e32 v46, vcc, s54, v28
	v_pk_fma_f32 v[56:57], v[14:15], v[48:49], v[26:27]
	s_nop 0
	v_addc_co_u32_e32 v47, vcc, -1, v29, vcc
	global_load_dwordx2 v[34:35], v[28:29], off
	global_load_dwordx2 v[26:27], v[28:29], off offset:-2560
	global_load_dwordx2 v[24:25], v[22:23], off
	s_nop 0
	global_load_dwordx2 v[22:23], v[30:31], off
	global_load_dwordx2 v[36:37], v[28:29], off offset:2048
	s_nop 0
	global_load_dwordx2 v[32:33], v[32:33], off
	s_nop 0
	global_load_dwordx2 v[30:31], v[46:47], off offset:-2560
	global_load_dwordx2 v[28:29], v[46:47], off offset:-512
	v_pk_mul_f32 v[54:55], v[0:1], v[58:59]
	v_pk_mul_f32 v[60:61], v[2:3], v[56:57]
	v_pk_mul_f32 v[50:51], v[54:55], v[54:55]
	v_pk_mul_f32 v[48:49], v[60:61], v[60:61]
	v_lshlrev_b32_e32 v21, 16, v38
	v_pk_mov_b32 v[52:53], v[50:51], v[48:49] op_sel:[1,0]
	v_mov_b32_e32 v51, v49
	v_mul_f32_e32 v21, 0xbfb8aa3b, v21
	v_pk_add_f32 v[48:49], v[52:53], v[50:51]
	v_exp_f32_e32 v46, v21
	v_add_f32_e32 v21, v48, v49
	v_lshlrev_b32_e32 v62, 16, v39
	v_mul_f32_e32 v49, 0xbfb8aa3b, v62
	v_add_f32_dpp v21, v21, v21 quad_perm:[1,0,3,2] row_mask:0xf bank_mask:0xf bound_ctrl:1
	v_and_b32_e32 v47, 0xffff0000, v38
	v_and_b32_e32 v63, 0xffff0000, v39
	v_add_f32_dpp v21, v21, v21 quad_perm:[2,3,0,1] row_mask:0xf bank_mask:0xf bound_ctrl:1
	v_lshlrev_b32_e32 v38, 16, v40
	v_and_b32_e32 v39, 0xffff0000, v40
	v_add_f32_dpp v21, v21, v21 row_half_mirror row_mask:0xf bank_mask:0xf bound_ctrl:1
	v_lshlrev_b32_e32 v40, 16, v41
	v_and_b32_e32 v41, 0xffff0000, v41
	v_add_f32_dpp v21, v21, v21 row_mirror row_mask:0xf bank_mask:0xf bound_ctrl:1
	v_mul_f32_e32 v47, 0xbfb8aa3b, v47
	v_exp_f32_e32 v47, v47
	v_sqrt_f32_e32 v21, v21
	s_nop 0
	v_max_f32_e32 v21, 0x2b8cbccc, v21
	v_exp_f32_e32 v48, v49
	v_mul_f32_e32 v49, 0xbfb8aa3b, v63
	v_exp_f32_e32 v49, v49
	v_rcp_f32_e32 v62, v21
	s_nop 0
	v_mul_f32_e32 v62, -1.0, v62
	v_pk_add_f32 v[50:51], v[40:41], -1.0 op_sel_hi:[1,0]
	v_pk_add_f32 v[52:53], v[38:39], -1.0 op_sel_hi:[1,0]
	v_pk_fma_f32 v[50:51], v[6:7], v[50:51], 1.0 op_sel_hi:[1,1,0]
	v_pk_fma_f32 v[64:65], v[4:5], v[52:53], 1.0 op_sel_hi:[1,1,0]
	v_pk_mul_f32 v[54:55], v[54:55], v[62:63] op_sel_hi:[1,0]
	v_pk_mul_f32 v[52:53], v[56:57], v[50:51]
	v_pk_mul_f32 v[50:51], v[58:59], v[64:65]
	v_pk_mul_f32 v[56:57], v[60:61], v[62:63] op_sel_hi:[1,0]
	v_pk_mul_f32 v[58:59], v[54:55], v[38:39] neg_lo:[1,0] neg_hi:[1,0]
	v_pk_mul_f32 v[60:61], v[56:57], v[40:41] neg_lo:[1,0] neg_hi:[1,0]
	v_mov_b32_e32 v40, v58
	v_mov_b32_e32 v41, v51
	v_pk_mov_b32 v[38:39], v[58:59], v[50:51] op_sel:[1,0]
	v_pk_mul_f32 v[40:41], v[66:67], v[40:41]
	v_pk_mul_f32 v[62:63], v[66:67], v[46:47]
	v_pk_fma_f32 v[38:39], v[66:67], v[38:39], v[40:41] op_sel:[1,0,0] op_sel_hi:[0,1,1]
	v_mov_b32_e32 v66, v60
	v_mov_b32_e32 v67, v53
	v_pk_mov_b32 v[40:41], v[60:61], v[52:53] op_sel:[1,0]
	v_pk_mul_f32 v[66:67], v[88:89], v[66:67]
	v_pk_mul_f32 v[64:65], v[88:89], v[48:49]
	v_pk_fma_f32 v[40:41], v[88:89], v[40:41], v[66:67] op_sel:[1,0,0] op_sel_hi:[0,1,1]
	v_pk_add_f32 v[38:39], v[38:39], v[40:41]
	ds_write_b128 v139, v[54:57]
	ds_write_b128 v139, v[62:65] offset:8192
	ds_write_b128 v139, v[46:49] offset:16384
	ds_write_b128 v139, v[58:61] offset:24576
	ds_write_b128 v139, v[50:53] offset:32768
	ds_write_b128 v139, v[42:45] offset:40960
	v_mov_b32_dpp v40, v38 quad_perm:[1,0,3,2] row_mask:0xf bank_mask:0xf bound_ctrl:1
	v_mov_b32_dpp v41, v39 quad_perm:[1,0,3,2] row_mask:0xf bank_mask:0xf bound_ctrl:1
	v_pk_add_f32 v[38:39], v[38:39], v[40:41]
	s_nop 1
	v_mov_b32_dpp v40, v38 quad_perm:[2,3,0,1] row_mask:0xf bank_mask:0xf bound_ctrl:1
	v_mov_b32_dpp v41, v39 quad_perm:[2,3,0,1] row_mask:0xf bank_mask:0xf bound_ctrl:1
	v_pk_add_f32 v[38:39], v[38:39], v[40:41]
	s_nop 1
	v_mov_b32_dpp v40, v38 row_half_mirror row_mask:0xf bank_mask:0xf bound_ctrl:1
	v_mov_b32_dpp v41, v39 row_half_mirror row_mask:0xf bank_mask:0xf bound_ctrl:1
	v_pk_add_f32 v[38:39], v[38:39], v[40:41]
	s_nop 1
	v_mov_b32_dpp v40, v38 row_mirror row_mask:0xf bank_mask:0xf bound_ctrl:1
	v_mov_b32_dpp v41, v39 row_mirror row_mask:0xf bank_mask:0xf bound_ctrl:1
	s_and_saveexec_b64 s[0:1], s[2:3]
	v_pk_add_f32 v[38:39], v[38:39], v[40:41]
	ds_write_b64 v140, v[38:39]
	s_or_b64 exec, exec, s[0:1]
	s_waitcnt vmcnt(7)
; __device__ __forceinline__ f32x4 unpack4(u32x2 u) { return (f32x4){__uint_as_float(u.x << 16), __uint_as_float(u.x & 0xffff0000u), __uint_as_float(u.y << 16), __uint_as_float(u.y & 0xffff0000u)}; }
; template <int ph>
; __device__ __forceinline__ void run_phase(const Args& args, LAS unsigned char* lds, const int G, const int bx, const bool fin = true) {
;     ...
;                     const f32x4 pr = unpack4(q_r[it]), pk = unpack4(q_k[it]), pv = unpack4(q_v[it]);
;                     const f32x4 r = pr + (unpack4(q_rp[it]) - pr) * mu_r, k = pk + (unpack4(q_kp[it]) - pk) * mu_k, v = pv + (unpack4(q_vp[it]) - pv) * mu_v;
	v_lshlrev_b32_e32 v38, 16, v34
	v_and_b32_e32 v39, 0xffff0000, v34
	v_lshlrev_b32_e32 v34, 16, v35
	v_and_b32_e32 v35, 0xffff0000, v35
	s_waitcnt vmcnt(1)
	v_lshlrev_b32_e32 v21, 16, v30
	v_and_b32_e32 v44, 0xffff0000, v30
	v_lshlrev_b32_e32 v30, 16, v31
	v_and_b32_e32 v31, 0xffff0000, v31
	v_sub_f32_e32 v31, v31, v35
	v_sub_f32_e32 v30, v30, v34
	v_lshlrev_b32_e32 v40, 16, v36
	v_and_b32_e32 v41, 0xffff0000, v36
	v_lshlrev_b32_e32 v36, 16, v37
	v_and_b32_e32 v37, 0xffff0000, v37
	v_sub_f32_e32 v45, v44, v39
	v_sub_f32_e32 v44, v21, v38
	v_pk_fma_f32 v[52:53], v[18:19], v[30:31], v[34:35]
	s_waitcnt vmcnt(0)
; #define LAS __attribute__((address_space(3)))
; __device__ __forceinline__ f32x4 unpack4(u32x2 u) { return (f32x4){__uint_as_float(u.x << 16), __uint_as_float(u.x & 0xffff0000u), __uint_as_float(u.y << 16), __uint_as_float(u.y & 0xffff0000u)}; }
; __device__ __forceinline__ float dot4(f32x4 a, f32x4 b) { return (a.x * b.x + a.y * b.y) + (a.z * b.z + a.w * b.w); }
; template <int ph>
; __device__ __forceinline__ void run_phase(const Args& args, LAS unsigned char* lds, const int G, const int bx, const bool fin = true) {
;     ...
;             auto derive = [&](int buf) {
;                 LAS float* V = VECb + buf * VB;
; #pragma unroll
;                 for (int it = 0; it < 2; ++it) {
;                     const int tt = tt0 + 16 * it;
;                     const f32x4 pr = unpack4(q_r[it]), pk = unpack4(q_k[it]), pv = unpack4(q_v[it]);
;                     const f32x4 r = pr + (unpack4(q_rp[it]) - pr) * mu_r, k = pk + (unpack4(q_kp[it]) - pk) * mu_k, v = pv + (unpack4(q_vp[it]) - pv) * mu_v;
;                     const f32x4 e = unpack4(q_e[it]), a = unpack4(q_a[it]);
;                     const f32x4 w = (f32x4){__expf(-e[0]), __expf(-e[1]), __expf(-e[2]), __expf(-e[3])};
;                     f32x4 kk = k * kkc; const float n2 = red16(dot4(kk, kk)); kk = kk * (1.0f / fmaxf(sqrtf(n2), 1e-12f));
;                     const f32x4 kp = k * (1.0f + (a - 1.0f) * kac), bv = kk * a, wrv = w * r;
;                     const float br = red16(dot4(bv, r)), kr = red16(dot4(kp, r));
;                     const int o = tt * 64 + 4 * cgq;
;                     *(LAS f32x4*)(V + 0 * TC * 64 + o) = -kk; *(LAS f32x4*)(V + 1 * TC * 64 + o) = wrv; *(LAS f32x4*)(V + 2 * TC * 64 + o) = w;
;                     *(LAS f32x4*)(V + 3 * TC * 64 + o) = bv; *(LAS f32x4*)(V + 4 * TC * 64 + o) = kp; *(LAS f32x4*)(V + 5 * TC * 64 + o) = v;
;                     if (cgq == 0) *(LAS f32x2*)(SCb + buf * TC * 2 + 2 * tt) = (f32x2){br, kr};
;                 }
;             };
	v_lshlrev_b32_e32 v21, 16, v28
	v_and_b32_e32 v28, 0xffff0000, v28
	v_lshlrev_b32_e32 v30, 16, v29
	v_and_b32_e32 v31, 0xffff0000, v29
	v_lshlrev_b32_e32 v42, 16, v32
	v_and_b32_e32 v43, 0xffff0000, v32
	v_sub_f32_e32 v29, v28, v41
	v_sub_f32_e32 v28, v21, v40
	v_sub_f32_e32 v31, v31, v37
	v_sub_f32_e32 v30, v30, v36
	v_lshlrev_b32_e32 v21, 16, v26
	v_and_b32_e32 v26, 0xffff0000, v26
	v_lshlrev_b32_e32 v32, 16, v33
	v_and_b32_e32 v33, 0xffff0000, v33
	v_pk_fma_f32 v[50:51], v[16:17], v[44:45], v[38:39]
	v_pk_fma_f32 v[34:35], v[14:15], v[30:31], v[36:37]
	v_pk_fma_f32 v[38:39], v[12:13], v[28:29], v[40:41]
	v_lshlrev_b32_e32 v28, 16, v27
	v_and_b32_e32 v29, 0xffff0000, v27
	v_sub_f32_e32 v27, v26, v43
	v_sub_f32_e32 v26, v21, v42
	v_sub_f32_e32 v29, v29, v33
	v_sub_f32_e32 v28, v28, v32
	v_pk_fma_f32 v[26:27], v[8:9], v[26:27], v[42:43]
	v_pk_mul_f32 v[42:43], v[0:1], v[38:39]
	v_pk_mul_f32 v[40:41], v[2:3], v[34:35]
	v_pk_fma_f32 v[28:29], v[10:11], v[28:29], v[32:33]
	v_pk_mul_f32 v[32:33], v[40:41], v[40:41]
	v_pk_mul_f32 v[36:37], v[42:43], v[42:43]
	v_lshlrev_b32_e32 v21, 16, v24
	v_pk_mov_b32 v[44:45], v[36:37], v[32:33] op_sel:[1,0]
	v_mov_b32_e32 v37, v33
	v_mul_f32_e32 v21, 0xbfb8aa3b, v21
	v_pk_add_f32 v[32:33], v[44:45], v[36:37]
	v_exp_f32_e32 v30, v21
	v_add_f32_e32 v21, v32, v33
	v_lshlrev_b32_e32 v46, 16, v25
	v_mul_f32_e32 v33, 0xbfb8aa3b, v46
	v_add_f32_dpp v21, v21, v21 quad_perm:[1,0,3,2] row_mask:0xf bank_mask:0xf bound_ctrl:1
	v_and_b32_e32 v31, 0xffff0000, v24
	v_and_b32_e32 v47, 0xffff0000, v25
	v_add_f32_dpp v21, v21, v21 quad_perm:[2,3,0,1] row_mask:0xf bank_mask:0xf bound_ctrl:1
	v_lshlrev_b32_e32 v24, 16, v22
	v_and_b32_e32 v25, 0xffff0000, v22
	v_add_f32_dpp v21, v21, v21 row_half_mirror row_mask:0xf bank_mask:0xf bound_ctrl:1
	v_lshlrev_b32_e32 v22, 16, v23
	v_and_b32_e32 v23, 0xffff0000, v23
	v_add_f32_dpp v21, v21, v21 row_mirror row_mask:0xf bank_mask:0xf bound_ctrl:1
	v_mul_f32_e32 v31, 0xbfb8aa3b, v31
	v_exp_f32_e32 v31, v31
	v_sqrt_f32_e32 v21, v21
	s_nop 0
	v_max_f32_e32 v21, 0x2b8cbccc, v21
	v_exp_f32_e32 v32, v33
	v_mul_f32_e32 v33, 0xbfb8aa3b, v47
	v_exp_f32_e32 v33, v33
	v_rcp_f32_e32 v46, v21
	s_nop 0
	v_mul_f32_e32 v46, -1.0, v46
	v_pk_add_f32 v[36:37], v[22:23], -1.0 op_sel_hi:[1,0]
	v_pk_add_f32 v[44:45], v[24:25], -1.0 op_sel_hi:[1,0]
	v_pk_fma_f32 v[36:37], v[6:7], v[36:37], 1.0 op_sel_hi:[1,1,0]
	v_pk_fma_f32 v[44:45], v[4:5], v[44:45], 1.0 op_sel_hi:[1,1,0]
	v_pk_mul_f32 v[36:37], v[34:35], v[36:37]
	v_pk_mul_f32 v[34:35], v[38:39], v[44:45]
	v_pk_mul_f32 v[38:39], v[42:43], v[46:47] op_sel_hi:[1,0]
	v_pk_mul_f32 v[40:41], v[40:41], v[46:47] op_sel_hi:[1,0]
	v_pk_mul_f32 v[42:43], v[38:39], v[24:25] neg_lo:[1,0] neg_hi:[1,0]
	v_mov_b32_e32 v25, v35
	v_mov_b32_e32 v24, v42
	v_pk_mul_f32 v[44:45], v[40:41], v[22:23] neg_lo:[1,0] neg_hi:[1,0]
	v_pk_mov_b32 v[22:23], v[42:43], v[34:35] op_sel:[1,0]
	v_pk_mul_f32 v[24:25], v[50:51], v[24:25]
	v_pk_mul_f32 v[46:47], v[50:51], v[30:31]
	v_pk_fma_f32 v[22:23], v[50:51], v[22:23], v[24:25] op_sel:[1,0,0] op_sel_hi:[0,1,1]
	v_mov_b32_e32 v50, v44
	v_mov_b32_e32 v51, v37
	v_pk_mov_b32 v[24:25], v[44:45], v[36:37] op_sel:[1,0]
	v_pk_mul_f32 v[50:51], v[52:53], v[50:51]
	v_pk_mul_f32 v[48:49], v[52:53], v[32:33]
	v_pk_fma_f32 v[24:25], v[52:53], v[24:25], v[50:51] op_sel:[1,0,0] op_sel_hi:[0,1,1]
	v_pk_add_f32 v[22:23], v[22:23], v[24:25]
	ds_write_b128 v142, v[38:41]
	ds_write_b128 v142, v[46:49] offset:8192
	ds_write_b128 v142, v[30:33] offset:16384
	ds_write_b128 v142, v[42:45] offset:24576
	ds_write_b128 v142, v[34:37] offset:32768
	ds_write_b128 v142, v[26:29] offset:40960
	v_mov_b32_dpp v24, v22 quad_perm:[1,0,3,2] row_mask:0xf bank_mask:0xf bound_ctrl:1
	v_mov_b32_dpp v25, v23 quad_perm:[1,0,3,2] row_mask:0xf bank_mask:0xf bound_ctrl:1
	v_pk_add_f32 v[22:23], v[22:23], v[24:25]
	s_nop 1
	v_mov_b32_dpp v24, v22 quad_perm:[2,3,0,1] row_mask:0xf bank_mask:0xf bound_ctrl:1
	v_mov_b32_dpp v25, v23 quad_perm:[2,3,0,1] row_mask:0xf bank_mask:0xf bound_ctrl:1
	v_pk_add_f32 v[22:23], v[22:23], v[24:25]
	s_nop 1
	v_mov_b32_dpp v24, v22 row_half_mirror row_mask:0xf bank_mask:0xf bound_ctrl:1
	v_mov_b32_dpp v25, v23 row_half_mirror row_mask:0xf bank_mask:0xf bound_ctrl:1
	v_pk_add_f32 v[22:23], v[22:23], v[24:25]
	s_nop 1
	v_mov_b32_dpp v24, v22 row_mirror row_mask:0xf bank_mask:0xf bound_ctrl:1
	v_mov_b32_dpp v25, v23 row_mirror row_mask:0xf bank_mask:0xf bound_ctrl:1
	s_and_saveexec_b64 s[0:1], s[2:3]
	v_pk_add_f32 v[22:23], v[22:23], v[24:25]
	ds_write_b64 v143, v[22:23]
	s_or_b64 exec, exec, s[0:1]
	v_or_b32_e32 v22, s42, v76
	v_mov_b64_e32 v[24:25], s[8:9]
	v_mad_u64_u32 v[26:27], s[0:1], v22, s52, v[24:25]
	v_mad_i32_i24 v27, s43, v153, v27
	v_mov_b32_e32 v21, v73
	v_lshl_add_u64 v[26:27], v[26:27], 0, v[20:21]
	v_add_co_u32_e32 v28, vcc, s53, v26
	v_mov_b32_e32 v23, s43
	s_nop 0
	v_addc_co_u32_e32 v29, vcc, 0, v27, vcc
	v_add_co_u32_e32 v30, vcc, s54, v26
	v_lshlrev_b64 v[22:23], 11, v[22:23]
	s_nop 0
	v_addc_co_u32_e32 v31, vcc, -1, v27, vcc
	global_load_dwordx2 v[90:91], v[26:27], off
	global_load_dwordx2 v[92:93], v[26:27], off offset:2048
	global_load_dwordx2 v[88:89], v[28:29], off
	global_load_dwordx2 v[100:101], v[26:27], off offset:-2560
	v_lshl_add_u64 v[26:27], s[20:21], 0, v[22:23]
	v_lshl_add_u64 v[22:23], s[22:23], 0, v[22:23]
	v_lshl_add_u64 v[22:23], v[22:23], 0, v[20:21]
	v_lshl_add_u64 v[26:27], v[26:27], 0, v[20:21]
	global_load_dwordx2 v[98:99], v[30:31], off offset:-2560
	global_load_dwordx2 v[96:97], v[30:31], off offset:-512
	global_load_dwordx2 v[94:95], v[26:27], off
	global_load_dwordx2 v[102:103], v[22:23], off
	v_or_b32_e32 v22, s42, v78
	v_mad_u64_u32 v[24:25], s[0:1], v22, s52, v[24:25]
	v_mad_i32_i24 v25, s43, v153, v25
	v_lshl_add_u64 v[24:25], v[24:25], 0, v[20:21]
	v_add_co_u32_e32 v26, vcc, s53, v24
	v_mov_b32_e32 v23, s43
	s_nop 0
	v_addc_co_u32_e32 v27, vcc, 0, v25, vcc
	v_add_co_u32_e32 v28, vcc, 0xfffff000, v24
	v_lshlrev_b64 v[22:23], 11, v[22:23]
	s_nop 0
	v_addc_co_u32_e32 v29, vcc, -1, v25, vcc
	global_load_dwordx2 v[108:109], v[24:25], off
	global_load_dwordx2 v[104:105], v[24:25], off offset:2048
	global_load_dwordx2 v[106:107], v[26:27], off
	global_load_dwordx2 v[110:111], v[24:25], off offset:-2560
	v_lshl_add_u64 v[24:25], s[20:21], 0, v[22:23]
	v_lshl_add_u64 v[22:23], s[22:23], 0, v[22:23]
	v_lshl_add_u64 v[24:25], v[24:25], 0, v[20:21]
	v_lshl_add_u64 v[20:21], v[22:23], 0, v[20:21]
	global_load_dwordx2 v[114:115], v[28:29], off offset:-2560
	global_load_dwordx2 v[112:113], v[28:29], off offset:-512
	global_load_dwordx2 v[118:119], v[24:25], off
	global_load_dwordx2 v[116:117], v[20:21], off

; #define LAS __attribute__((address_space(3)))
; __device__ __forceinline__ f32x4 unpack4(u32x2 u) { return (f32x4){__uint_as_float(u.x << 16), __uint_as_float(u.x & 0xffff0000u), __uint_as_float(u.y << 16), __uint_as_float(u.y & 0xffff0000u)}; }
; __device__ __forceinline__ float dot4(f32x4 a, f32x4 b) { return (a.x * b.x + a.y * b.y) + (a.z * b.z + a.w * b.w); }
; template <int ph>
; __device__ __forceinline__ void run_phase(const Args& args, LAS unsigned char* lds, const int G, const int bx, const bool fin = true) {
;     ...
;             auto derive = [&](int buf) {
;                 LAS float* V = VECb + buf * VB;
; #pragma unroll
;                 for (int it = 0; it < 2; ++it) {
;                     const int tt = tt0 + 16 * it;
;                     const f32x4 pr = unpack4(q_r[it]), pk = unpack4(q_k[it]), pv = unpack4(q_v[it]);
;                     const f32x4 r = pr + (unpack4(q_rp[it]) - pr) * mu_r, k = pk + (unpack4(q_kp[it]) - pk) * mu_k, v = pv + (unpack4(q_vp[it]) - pv) * mu_v;
;                     const f32x4 e = unpack4(q_e[it]), a = unpack4(q_a[it]);
;                     const f32x4 w = (f32x4){__expf(-e[0]), __expf(-e[1]), __expf(-e[2]), __expf(-e[3])};
;                     f32x4 kk = k * kkc; const float n2 = red16(dot4(kk, kk)); kk = kk * (1.0f / fmaxf(sqrtf(n2), 1e-12f));
;                     const f32x4 kp = k * (1.0f + (a - 1.0f) * kac), bv = kk * a, wrv = w * r;
;                     const float br = red16(dot4(bv, r)), kr = red16(dot4(kp, r));
;                     const int o = tt * 64 + 4 * cgq;
;                     *(LAS f32x4*)(V + 0 * TC * 64 + o) = -kk; *(LAS f32x4*)(V + 1 * TC * 64 + o) = wrv; *(LAS f32x4*)(V + 2 * TC * 64 + o) = w;
;                     *(LAS f32x4*)(V + 3 * TC * 64 + o) = bv; *(LAS f32x4*)(V + 4 * TC * 64 + o) = kp; *(LAS f32x4*)(V + 5 * TC * 64 + o) = v;
;                     if (cgq == 0) *(LAS f32x2*)(SCb + buf * TC * 2 + 2 * tt) = (f32x2){br, kr};
;                 }
;             };
.LBB0_1014:
	s_andn2_b64 vcc, exec, s[0:1]
	s_cbranch_vccnz .LBB0_1006
	s_waitcnt vmcnt(11) lgkmcnt(5)
	v_lshlrev_b32_e32 v28, 16, v90
	v_and_b32_e32 v29, 0xffff0000, v90
	v_lshlrev_b32_e32 v30, 16, v91
	v_and_b32_e32 v31, 0xffff0000, v91
	v_lshlrev_b32_e32 v42, 16, v98
	v_and_b32_e32 v43, 0xffff0000, v98
	v_lshlrev_b32_e32 v40, 16, v99
	v_and_b32_e32 v41, 0xffff0000, v99
	v_sub_f32_e32 v41, v41, v31
	v_sub_f32_e32 v40, v40, v30
	v_sub_f32_e32 v43, v43, v29
	v_sub_f32_e32 v42, v42, v28
	s_waitcnt vmcnt(10)
	v_lshlrev_b32_e32 v32, 16, v92
	v_and_b32_e32 v33, 0xffff0000, v92
	v_lshlrev_b32_e32 v34, 16, v93
	v_and_b32_e32 v35, 0xffff0000, v93
	v_pk_fma_f32 v[28:29], v[16:17], v[42:43], v[28:29]
	v_pk_fma_f32 v[30:31], v[18:19], v[40:41], v[30:31]
	v_lshlrev_b32_e32 v40, 16, v96
	v_and_b32_e32 v41, 0xffff0000, v96
	v_lshlrev_b32_e32 v42, 16, v97
	v_and_b32_e32 v43, 0xffff0000, v97
	v_sub_f32_e32 v41, v41, v33
	v_sub_f32_e32 v40, v40, v32
	v_sub_f32_e32 v43, v43, v35
	v_sub_f32_e32 v42, v42, v34
	v_lshlrev_b32_e32 v38, 16, v89
	v_and_b32_e32 v39, 0xffff0000, v89
	v_pk_fma_f32 v[42:43], v[14:15], v[42:43], v[34:35]
	v_pk_fma_f32 v[40:41], v[12:13], v[40:41], v[32:33]
	s_waitcnt vmcnt(9)
	v_lshlrev_b32_e32 v34, 16, v101
	v_and_b32_e32 v35, 0xffff0000, v101
	v_sub_f32_e32 v35, v35, v39
	v_sub_f32_e32 v34, v34, v38
	s_waitcnt lgkmcnt(4)
	v_pk_mul_f32 v[52:53], v[0:1], v[40:41]
	s_waitcnt lgkmcnt(3)
	v_pk_mul_f32 v[46:47], v[2:3], v[42:43]
	v_pk_fma_f32 v[34:35], v[10:11], v[34:35], v[38:39]
	v_pk_mul_f32 v[38:39], v[46:47], v[46:47]
	v_pk_mul_f32 v[50:51], v[52:53], v[52:53]
	s_xor_b32 s0, s61, 1
	v_pk_mov_b32 v[54:55], v[50:51], v[38:39] op_sel:[1,0]
	v_mov_b32_e32 v51, v39
	v_pk_add_f32 v[38:39], v[54:55], v[50:51]
	s_mul_i32 s1, s0, 0xc000
	v_add_f32_e32 v38, v38, v39
	s_add_i32 s62, s1, 0
	s_lshl_b32 s61, s0, 8
	v_add_f32_dpp v38, v38, v38 quad_perm:[1,0,3,2] row_mask:0xf bank_mask:0xf bound_ctrl:1
	v_lshlrev_b32_e32 v56, 16, v95
	v_mul_f32_e32 v50, 0xbfb8aa3b, v56
	v_add_f32_dpp v38, v38, v38 quad_perm:[2,3,0,1] row_mask:0xf bank_mask:0xf bound_ctrl:1
	v_and_b32_e32 v57, 0xffff0000, v95
	v_lshlrev_b32_e32 v36, 16, v88
	v_add_f32_dpp v38, v38, v38 row_half_mirror row_mask:0xf bank_mask:0xf bound_ctrl:1
	v_and_b32_e32 v37, 0xffff0000, v88
	v_lshlrev_b32_e32 v32, 16, v100
	v_add_f32_dpp v38, v38, v38 row_mirror row_mask:0xf bank_mask:0xf bound_ctrl:1
	v_and_b32_e32 v33, 0xffff0000, v100
	v_sub_f32_e32 v33, v33, v37
	v_sub_f32_e32 v32, v32, v36
	v_pk_fma_f32 v[32:33], v[8:9], v[32:33], v[36:37]
	v_lshlrev_b32_e32 v36, 16, v94
	v_and_b32_e32 v37, 0xffff0000, v94
	s_waitcnt vmcnt(7)
	v_lshlrev_b32_e32 v44, 16, v103
	v_and_b32_e32 v45, 0xffff0000, v103
	v_mul_f32_e32 v36, 0xbfb8aa3b, v36
	v_mul_f32_e32 v37, 0xbfb8aa3b, v37
	v_sqrt_f32_e32 v38, v38
	s_nop 0
	v_max_f32_e32 v51, 0x2b8cbccc, v38
	v_exp_f32_e32 v38, v50
	v_mul_f32_e32 v39, 0xbfb8aa3b, v57
	v_lshlrev_b32_e32 v48, 16, v102
	v_and_b32_e32 v49, 0xffff0000, v102
	v_exp_f32_e32 v36, v36
	v_exp_f32_e32 v37, v37
	v_rcp_f32_e32 v54, v51
	s_nop 0
	v_mul_f32_e32 v54, -1.0, v54
	v_pk_add_f32 v[50:51], v[44:45], -1.0 op_sel_hi:[1,0]
	v_pk_add_f32 v[56:57], v[48:49], -1.0 op_sel_hi:[1,0]
	v_pk_fma_f32 v[50:51], v[6:7], v[50:51], 1.0 op_sel_hi:[1,1,0]
	v_pk_mul_f32 v[46:47], v[46:47], v[54:55] op_sel_hi:[1,0]
	v_exp_f32_e32 v39, v39
	v_pk_fma_f32 v[56:57], v[4:5], v[56:57], 1.0 op_sel_hi:[1,1,0]
	v_pk_mul_f32 v[42:43], v[50:51], v[42:43]
	v_pk_mul_f32 v[50:51], v[46:47], v[44:45] neg_lo:[1,0] neg_hi:[1,0]
	v_pk_mul_f32 v[44:45], v[52:53], v[54:55] op_sel_hi:[1,0]
	v_pk_mul_f32 v[40:41], v[56:57], v[40:41]
	v_pk_mul_f32 v[48:49], v[44:45], v[48:49] neg_lo:[1,0] neg_hi:[1,0]
	v_pk_mul_f32 v[52:53], v[36:37], v[28:29]
	v_pk_mov_b32 v[56:57], v[28:29], v[40:41] op_sel:[1,0]
	v_pk_mov_b32 v[58:59], v[48:49], v[28:29] op_sel:[1,0]
	v_mov_b32_e32 v60, v28
	v_mov_b32_e32 v61, v41
	v_mov_b32_e32 v28, v48
	v_pk_mul_f32 v[28:29], v[60:61], v[28:29]
	v_pk_mul_f32 v[54:55], v[38:39], v[30:31]
	v_pk_fma_f32 v[28:29], v[56:57], v[58:59], v[28:29]
	v_pk_mov_b32 v[56:57], v[30:31], v[42:43] op_sel:[1,0]
	v_pk_mov_b32 v[58:59], v[50:51], v[30:31] op_sel:[1,0]
	v_mov_b32_e32 v60, v30
	v_mov_b32_e32 v61, v43
	v_mov_b32_e32 v30, v50
	v_pk_mul_f32 v[30:31], v[60:61], v[30:31]
	s_nop 0
	v_pk_fma_f32 v[30:31], v[56:57], v[58:59], v[30:31]
	v_lshl_add_u32 v56, v138, 2, s62
	v_pk_add_f32 v[28:29], v[28:29], v[30:31]
	ds_write_b128 v56, v[44:47]
	ds_write_b128 v56, v[52:55] offset:8192
	ds_write_b128 v56, v[36:39] offset:16384
	ds_write_b128 v56, v[48:51] offset:24576
	ds_write_b128 v56, v[40:43] offset:32768
	ds_write_b128 v56, v[32:35] offset:40960
	v_mov_b32_dpp v30, v28 quad_perm:[1,0,3,2] row_mask:0xf bank_mask:0xf bound_ctrl:1
	v_mov_b32_dpp v31, v29 quad_perm:[1,0,3,2] row_mask:0xf bank_mask:0xf bound_ctrl:1
	v_pk_add_f32 v[28:29], v[28:29], v[30:31]
	s_nop 1
	v_mov_b32_dpp v30, v28 quad_perm:[2,3,0,1] row_mask:0xf bank_mask:0xf bound_ctrl:1
	v_mov_b32_dpp v31, v29 quad_perm:[2,3,0,1] row_mask:0xf bank_mask:0xf bound_ctrl:1
	v_pk_add_f32 v[28:29], v[28:29], v[30:31]
	s_nop 1
	v_mov_b32_dpp v30, v28 row_half_mirror row_mask:0xf bank_mask:0xf bound_ctrl:1
	v_mov_b32_dpp v31, v29 row_half_mirror row_mask:0xf bank_mask:0xf bound_ctrl:1
	v_pk_add_f32 v[28:29], v[28:29], v[30:31]
	s_nop 1
	v_mov_b32_dpp v30, v28 row_mirror row_mask:0xf bank_mask:0xf bound_ctrl:1
	v_mov_b32_dpp v31, v29 row_mirror row_mask:0xf bank_mask:0xf bound_ctrl:1
	s_and_saveexec_b64 s[0:1], s[2:3]
	v_pk_add_f32 v[28:29], v[28:29], v[30:31]
	v_add_u32_e32 v30, s61, v140
	ds_write_b64 v30, v[28:29]
	s_or_b64 exec, exec, s[0:1]
	s_waitcnt vmcnt(3)
; #define LAS __attribute__((address_space(3)))
; __device__ __forceinline__ f32x4 unpack4(u32x2 u) { return (f32x4){__uint_as_float(u.x << 16), __uint_as_float(u.x & 0xffff0000u), __uint_as_float(u.y << 16), __uint_as_float(u.y & 0xffff0000u)}; }
; __device__ __forceinline__ float dot4(f32x4 a, f32x4 b) { return (a.x * b.x + a.y * b.y) + (a.z * b.z + a.w * b.w); }
; template <int ph>
; __device__ __forceinline__ void run_phase(const Args& args, LAS unsigned char* lds, const int G, const int bx, const bool fin = true) {
;     ...
;             auto derive = [&](int buf) {
;                 LAS float* V = VECb + buf * VB;
; #pragma unroll
;                 for (int it = 0; it < 2; ++it) {
;                     const int tt = tt0 + 16 * it;
;                     const f32x4 pr = unpack4(q_r[it]), pk = unpack4(q_k[it]), pv = unpack4(q_v[it]);
;                     const f32x4 r = pr + (unpack4(q_rp[it]) - pr) * mu_r, k = pk + (unpack4(q_kp[it]) - pk) * mu_k, v = pv + (unpack4(q_vp[it]) - pv) * mu_v;
;                     const f32x4 e = unpack4(q_e[it]), a = unpack4(q_a[it]);
;                     const f32x4 w = (f32x4){__expf(-e[0]), __expf(-e[1]), __expf(-e[2]), __expf(-e[3])};
;                     f32x4 kk = k * kkc; const float n2 = red16(dot4(kk, kk)); kk = kk * (1.0f / fmaxf(sqrtf(n2), 1e-12f));
;                     const f32x4 kp = k * (1.0f + (a - 1.0f) * kac), bv = kk * a, wrv = w * r;
;                     const float br = red16(dot4(bv, r)), kr = red16(dot4(kp, r));
;                     const int o = tt * 64 + 4 * cgq;
;                     *(LAS f32x4*)(V + 0 * TC * 64 + o) = -kk; *(LAS f32x4*)(V + 1 * TC * 64 + o) = wrv; *(LAS f32x4*)(V + 2 * TC * 64 + o) = w;
;                     *(LAS f32x4*)(V + 3 * TC * 64 + o) = bv; *(LAS f32x4*)(V + 4 * TC * 64 + o) = kp; *(LAS f32x4*)(V + 5 * TC * 64 + o) = v;
;                     if (cgq == 0) *(LAS f32x2*)(SCb + buf * TC * 2 + 2 * tt) = (f32x2){br, kr};
;                 }
;             };
	v_lshlrev_b32_e32 v28, 16, v108
	v_and_b32_e32 v29, 0xffff0000, v108
	v_lshlrev_b32_e32 v30, 16, v109
	v_and_b32_e32 v31, 0xffff0000, v109
	v_lshlrev_b32_e32 v42, 16, v114
	v_and_b32_e32 v43, 0xffff0000, v114
	v_lshlrev_b32_e32 v40, 16, v115
	v_and_b32_e32 v41, 0xffff0000, v115
	v_sub_f32_e32 v41, v41, v31
	v_sub_f32_e32 v40, v40, v30
	v_sub_f32_e32 v43, v43, v29
	v_sub_f32_e32 v42, v42, v28
	v_lshlrev_b32_e32 v32, 16, v104
	v_and_b32_e32 v33, 0xffff0000, v104
	v_lshlrev_b32_e32 v34, 16, v105
	v_and_b32_e32 v35, 0xffff0000, v105
	v_pk_fma_f32 v[28:29], v[16:17], v[42:43], v[28:29]
	v_pk_fma_f32 v[30:31], v[18:19], v[40:41], v[30:31]
	v_lshlrev_b32_e32 v40, 16, v112
	v_and_b32_e32 v41, 0xffff0000, v112
	v_lshlrev_b32_e32 v42, 16, v113
	v_and_b32_e32 v43, 0xffff0000, v113
	v_sub_f32_e32 v41, v41, v33
	v_sub_f32_e32 v40, v40, v32
	v_sub_f32_e32 v43, v43, v35
	v_sub_f32_e32 v42, v42, v34
	v_lshlrev_b32_e32 v38, 16, v107
	v_and_b32_e32 v39, 0xffff0000, v107
	v_pk_fma_f32 v[42:43], v[14:15], v[42:43], v[34:35]
	v_pk_fma_f32 v[40:41], v[12:13], v[40:41], v[32:33]
	s_waitcnt vmcnt(2)
	v_lshlrev_b32_e32 v34, 16, v111
	v_and_b32_e32 v35, 0xffff0000, v111
	v_sub_f32_e32 v35, v35, v39
	v_sub_f32_e32 v34, v34, v38
	v_pk_mul_f32 v[52:53], v[0:1], v[40:41]
	v_pk_mul_f32 v[46:47], v[2:3], v[42:43]
	v_pk_fma_f32 v[34:35], v[10:11], v[34:35], v[38:39]
	v_pk_mul_f32 v[38:39], v[46:47], v[46:47]
	v_pk_mul_f32 v[50:51], v[52:53], v[52:53]
	s_waitcnt vmcnt(1)
	v_lshlrev_b32_e32 v56, 16, v119
	v_pk_mov_b32 v[54:55], v[50:51], v[38:39] op_sel:[1,0]
	v_mov_b32_e32 v51, v39
	v_pk_add_f32 v[38:39], v[54:55], v[50:51]
	v_mul_f32_e32 v50, 0xbfb8aa3b, v56
	v_add_f32_e32 v38, v38, v39
	v_and_b32_e32 v57, 0xffff0000, v119
	v_lshlrev_b32_e32 v36, 16, v106
	v_add_f32_dpp v38, v38, v38 quad_perm:[1,0,3,2] row_mask:0xf bank_mask:0xf bound_ctrl:1
	v_and_b32_e32 v37, 0xffff0000, v106
	v_lshlrev_b32_e32 v32, 16, v110
	v_add_f32_dpp v38, v38, v38 quad_perm:[2,3,0,1] row_mask:0xf bank_mask:0xf bound_ctrl:1
	v_and_b32_e32 v33, 0xffff0000, v110
	v_sub_f32_e32 v33, v33, v37
	v_add_f32_dpp v38, v38, v38 row_half_mirror row_mask:0xf bank_mask:0xf bound_ctrl:1
	v_sub_f32_e32 v32, v32, v36
	v_pk_fma_f32 v[32:33], v[8:9], v[32:33], v[36:37]
	v_add_f32_dpp v38, v38, v38 row_mirror row_mask:0xf bank_mask:0xf bound_ctrl:1
	v_lshlrev_b32_e32 v36, 16, v118
	v_and_b32_e32 v37, 0xffff0000, v118
	s_waitcnt vmcnt(0)
	v_lshlrev_b32_e32 v44, 16, v117
	v_and_b32_e32 v45, 0xffff0000, v117
	v_mul_f32_e32 v36, 0xbfb8aa3b, v36
	v_mul_f32_e32 v37, 0xbfb8aa3b, v37
	v_lshlrev_b32_e32 v48, 16, v116
	v_and_b32_e32 v49, 0xffff0000, v116
	v_exp_f32_e32 v36, v36
	v_exp_f32_e32 v37, v37
	v_sqrt_f32_e32 v38, v38
	s_nop 0
	v_max_f32_e32 v51, 0x2b8cbccc, v38
	v_exp_f32_e32 v38, v50
	v_mul_f32_e32 v39, 0xbfb8aa3b, v57
	v_exp_f32_e32 v39, v39
	v_rcp_f32_e32 v54, v51
	s_nop 0
	v_mul_f32_e32 v54, -1.0, v54
	v_pk_add_f32 v[50:51], v[44:45], -1.0 op_sel_hi:[1,0]
	v_pk_add_f32 v[56:57], v[48:49], -1.0 op_sel_hi:[1,0]
	v_pk_fma_f32 v[50:51], v[6:7], v[50:51], 1.0 op_sel_hi:[1,1,0]
	v_pk_mul_f32 v[46:47], v[46:47], v[54:55] op_sel_hi:[1,0]
	v_pk_fma_f32 v[56:57], v[4:5], v[56:57], 1.0 op_sel_hi:[1,1,0]
	v_pk_mul_f32 v[42:43], v[50:51], v[42:43]
	v_pk_mul_f32 v[50:51], v[46:47], v[44:45] neg_lo:[1,0] neg_hi:[1,0]
	v_pk_mul_f32 v[44:45], v[52:53], v[54:55] op_sel_hi:[1,0]
	v_pk_mul_f32 v[40:41], v[56:57], v[40:41]
	v_pk_mul_f32 v[48:49], v[44:45], v[48:49] neg_lo:[1,0] neg_hi:[1,0]
	v_pk_mul_f32 v[52:53], v[36:37], v[28:29]
	v_pk_mov_b32 v[56:57], v[28:29], v[40:41] op_sel:[1,0]
	v_pk_mov_b32 v[58:59], v[48:49], v[28:29] op_sel:[1,0]
	v_mov_b32_e32 v60, v28
	v_mov_b32_e32 v61, v41
	v_mov_b32_e32 v28, v48
	v_pk_mul_f32 v[28:29], v[60:61], v[28:29]
	v_pk_mul_f32 v[54:55], v[38:39], v[30:31]
	v_pk_fma_f32 v[28:29], v[56:57], v[58:59], v[28:29]
	v_pk_mov_b32 v[56:57], v[30:31], v[42:43] op_sel:[1,0]
	v_pk_mov_b32 v[58:59], v[50:51], v[30:31] op_sel:[1,0]
	v_mov_b32_e32 v60, v30
	v_mov_b32_e32 v61, v43
	v_mov_b32_e32 v30, v50
	v_pk_mul_f32 v[30:31], v[60:61], v[30:31]
	s_nop 0
	v_pk_fma_f32 v[30:31], v[56:57], v[58:59], v[30:31]
	v_lshl_add_u32 v56, v141, 2, s62
	v_pk_add_f32 v[28:29], v[28:29], v[30:31]
	ds_write_b128 v56, v[44:47]
	ds_write_b128 v56, v[52:55] offset:8192
	ds_write_b128 v56, v[36:39] offset:16384
	ds_write_b128 v56, v[48:51] offset:24576
	ds_write_b128 v56, v[40:43] offset:32768
	ds_write_b128 v56, v[32:35] offset:40960
	v_mov_b32_dpp v30, v28 quad_perm:[1,0,3,2] row_mask:0xf bank_mask:0xf bound_ctrl:1
	v_mov_b32_dpp v31, v29 quad_perm:[1,0,3,2] row_mask:0xf bank_mask:0xf bound_ctrl:1
	v_pk_add_f32 v[28:29], v[28:29], v[30:31]
	s_nop 1
	v_mov_b32_dpp v30, v28 quad_perm:[2,3,0,1] row_mask:0xf bank_mask:0xf bound_ctrl:1
	v_mov_b32_dpp v31, v29 quad_perm:[2,3,0,1] row_mask:0xf bank_mask:0xf bound_ctrl:1
	v_pk_add_f32 v[28:29], v[28:29], v[30:31]
	s_nop 1
	v_mov_b32_dpp v30, v28 row_half_mirror row_mask:0xf bank_mask:0xf bound_ctrl:1
	v_mov_b32_dpp v31, v29 row_half_mirror row_mask:0xf bank_mask:0xf bound_ctrl:1
	v_pk_add_f32 v[28:29], v[28:29], v[30:31]
	s_nop 1
	v_mov_b32_dpp v30, v28 row_mirror row_mask:0xf bank_mask:0xf bound_ctrl:1
	v_mov_b32_dpp v31, v29 row_mirror row_mask:0xf bank_mask:0xf bound_ctrl:1
	s_and_saveexec_b64 s[0:1], s[2:3]
	v_pk_add_f32 v[28:29], v[28:29], v[30:31]
	v_add_u32_e32 v30, s61, v143
	ds_write_b64 v30, v[28:29]
	s_or_b64 exec, exec, s[0:1]
	s_cmp_gt_u32 s60, 61
	s_cbranch_scc1 .LBB0_1006
; template <int ph>
; __device__ __forceinline__ void run_phase(const Args& args, LAS unsigned char* lds, const int G, const int bx, const bool fin = true) {
;     ...
;             auto issue = [&](int chunk) {
; #pragma unroll
;                 for (int it = 0; it < 2; ++it) {
;                     const int tg = chunk * TC + tt0 + 16 * it; const size_t row = (size_t)b * T + tg; const bf16_t* base = PR + row * RP + chb;
;                     q_r[it] = *(const u32x2*)(base); q_k[it] = *(const u32x2*)(base + 1024); q_v[it] = *(const u32x2*)(base + 2048);
;                     if (tg > 0) { q_rp[it] = *(const u32x2*)(base - RP); q_kp[it] = *(const u32x2*)(base - RP + 1024); q_vp[it] = *(const u32x2*)(base - RP + 2048); }
;                     else { q_rp[it] = (u32x2){0u, 0u}; q_kp[it] = q_rp[it]; q_vp[it] = q_rp[it]; }
;                     q_e[it] = *(const u32x2*)(WD + row * D + chb); q_a[it] = *(const u32x2*)(AA + row * D + chb);
;                 }
	s_waitcnt lgkmcnt(14)
	v_lshl_add_u32 v72, s60, 5, v148
	v_lshl_add_u64 v[28:29], s[42:43], 0, v[72:73]
	v_mad_u64_u32 v[30:31], s[0:1], v28, s52, v[122:123]
	v_mov_b32_e32 v32, v31
	v_mad_u64_u32 v[32:33], s[0:1], v29, s52, v[32:33]
	v_add_co_u32_e32 v34, vcc, s53, v30
	v_lshlrev_b64 v[28:29], 11, v[28:29]
	s_nop 0
	v_addc_co_u32_e32 v35, vcc, 0, v32, vcc
	v_add_co_u32_e32 v36, vcc, s54, v30
	v_mov_b32_e32 v31, v32
	s_nop 0
	v_addc_co_u32_e32 v37, vcc, -1, v32, vcc
	v_lshl_add_u64 v[32:33], v[124:125], 0, v[28:29]
	v_or_b32_e32 v72, 16, v72
	global_load_dwordx2 v[88:89], v[34:35], off
	global_load_dwordx2 v[98:99], v[36:37], off offset:-2560
	global_load_dwordx2 v[96:97], v[36:37], off offset:-512
	global_load_dwordx2 v[94:95], v[32:33], off
	v_lshl_add_u64 v[32:33], s[42:43], 0, v[72:73]
	v_mad_u64_u32 v[34:35], s[0:1], v32, s52, v[122:123]
	v_mov_b32_e32 v36, v35
	v_mad_u64_u32 v[36:37], s[0:1], v33, s52, v[36:37]
	v_mov_b32_e32 v35, v36
	global_load_dwordx2 v[90:91], v[30:31], off
	global_load_dwordx2 v[92:93], v[30:31], off offset:2048
	global_load_dwordx2 v[100:101], v[30:31], off offset:-2560
	global_load_dwordx2 v[104:105], v[34:35], off offset:2048
	v_add_co_u32_e32 v30, vcc, s53, v34
	v_lshl_add_u64 v[28:29], v[126:127], 0, v[28:29]
	s_nop 0
	v_addc_co_u32_e32 v31, vcc, 0, v36, vcc
	v_add_co_u32_e32 v38, vcc, 0xfffff000, v34
	s_nop 1
	v_addc_co_u32_e32 v39, vcc, -1, v36, vcc
	global_load_dwordx2 v[102:103], v[28:29], off
	global_load_dwordx2 v[106:107], v[30:31], off
	global_load_dwordx2 v[114:115], v[38:39], off offset:-2560
	global_load_dwordx2 v[112:113], v[38:39], off offset:-512
	v_lshlrev_b64 v[28:29], 11, v[32:33]
	v_lshl_add_u64 v[30:31], v[124:125], 0, v[28:29]
	v_lshl_add_u64 v[28:29], v[126:127], 0, v[28:29]
	global_load_dwordx2 v[108:109], v[34:35], off
	global_load_dwordx2 v[110:111], v[34:35], off offset:-2560
	global_load_dwordx2 v[118:119], v[30:31], off
	global_load_dwordx2 v[116:117], v[28:29], off
	s_branch .LBB0_1006

; #define LAS __attribute__((address_space(3)))
; __device__ __forceinline__ f32x4 unpack4(u32x2 u) { return (f32x4){__uint_as_float(u.x << 16), __uint_as_float(u.x & 0xffff0000u), __uint_as_float(u.y << 16), __uint_as_float(u.y & 0xffff0000u)}; }
; __device__ __forceinline__ float dot4(f32x4 a, f32x4 b) { return (a.x * b.x + a.y * b.y) + (a.z * b.z + a.w * b.w); }
; template <int ph>
; __device__ __forceinline__ void run_phase(const Args& args, LAS unsigned char* lds, const int G, const int bx, const bool fin = true) {
;     ...
;                 const int i = un >> 4, h = un & 15, chb = h * 64 + 4 * cgq; const size_t row = (size_t)MP + i;
;                 const bf16_t* base = PR + row * RP + chb; const float* sb = state_shift + (size_t)i * RP + chb;
;                 const f32x4 pr = unpack4(*(const u32x2*)(base)), pk = unpack4(*(const u32x2*)(base + 1024)), pv = unpack4(*(const u32x2*)(base + 2048));
;                 const f32x4 r = pr + (*(const f32x4*)(sb) - pr) * *(const f32x4*)(shift_mu + chb), k = pk + (*(const f32x4*)(sb + 1024) - pk) * *(const f32x4*)(shift_mu + 1024 + chb),
;                             v = pv + (*(const f32x4*)(sb + 2048) - pv) * *(const f32x4*)(shift_mu + 2048 + chb);
;                 const f32x4 e = unpack4(*(const u32x2*)(WD + row * D + chb)), a = unpack4(*(const u32x2*)(AA + row * D + chb));
;                 const f32x4 w = (f32x4){__expf(-e[0]), __expf(-e[1]), __expf(-e[2]), __expf(-e[3])};
;                 f32x4 kk = k * *(const f32x4*)(k_k + chb); const float n2 = red16(dot4(kk, kk)); kk = kk * (1.0f / fmaxf(sqrtf(n2), 1e-12f));
;                 const f32x4 kp = k * (1.0f + (a - 1.0f) * *(const f32x4*)(k_a + chb)), bv = kk * a, wrv = w * r;
;                 const float br = red16(dot4(bv, r)), kr = red16(dot4(kp, r));
;                 if (lane < 16) *(LAS f32x4*)(V1 + 320 + 4 * cgq) = v;
.LBB0_1029:
	s_ashr_i32 s26, s11, 4
	s_and_b32 s0, s11, 15
	s_ashr_i32 s27, s26, 31
	v_lshl_or_b32 v0, s0, 6, v46
	s_add_u32 s0, s26, 0x4000
	s_addc_u32 s1, s27, 0
	s_mul_i32 s28, s0, 0x1a00
	v_readlane_b32 s52, v229, 0
	s_mul_hi_i32 s29, s0, 0x1a00
	s_add_u32 s28, s8, s28
	v_readlane_b32 s60, v229, 8
	v_readlane_b32 s61, v229, 9
	v_readlane_b32 s62, v229, 10
	v_readlane_b32 s63, v229, 11
	v_readlane_b32 s64, v229, 12
	v_readlane_b32 s65, v229, 13
	s_addc_u32 s29, s9, s29
	s_mul_i32 s42, s26, 0x3400
	v_readlane_b32 s66, v229, 14
	v_readlane_b32 s67, v229, 15
	s_mov_b64 s[60:61], s[64:65]
	s_mul_hi_i32 s43, s26, 0x3400
	s_add_u32 s42, s60, s42
	s_addc_u32 s43, s61, s43
	v_lshlrev_b64 v[26:27], 2, v[0:1]
	v_lshlrev_b32_e32 v20, 1, v0
	v_lshl_add_u64 v[22:23], s[42:43], 0, v[26:27]
	global_load_dwordx2 v[24:25], v20, s[28:29]
	v_add_co_u32_e32 v16, vcc, s39, v22
	global_load_dwordx2 v[42:43], v20, s[28:29] offset:2048
	global_load_dwordx4 v[8:11], v[22:23], off
	v_lshl_add_u64 v[12:13], s[36:37], 0, v[26:27]
	v_addc_co_u32_e32 v17, vcc, 0, v23, vcc
	global_load_dwordx4 v[12:15], v[12:13], off
	v_lshl_add_u64 v[28:29], s[6:7], 0, v[26:27]
	global_load_dwordx4 v[16:19], v[16:17], off
	s_lshl_b64 s[0:1], s[0:1], 11
	global_load_dwordx4 v[30:33], v[28:29], off
	v_lshl_add_u64 v[28:29], s[48:49], 0, v[26:27]
	global_load_dwordx4 v[34:37], v[28:29], off
	s_add_u32 s42, s20, s0
	s_addc_u32 s43, s21, s1
	s_add_u32 s0, s22, s0
	s_addc_u32 s1, s23, s1
	global_load_dwordx2 v[44:45], v20, s[0:1]
	v_lshl_add_u64 v[26:27], s[50:51], 0, v[26:27]
	global_load_dwordx4 v[38:41], v[26:27], off
	global_load_dwordx2 v[28:29], v20, s[42:43]
	v_readlane_b32 s53, v229, 1
	v_readlane_b32 s54, v229, 2
	v_readlane_b32 s55, v229, 3
	v_readlane_b32 s56, v229, 4
	v_readlane_b32 s57, v229, 5
	v_readlane_b32 s58, v229, 6
	v_readlane_b32 s59, v229, 7
	s_mov_b64 s[62:63], s[66:67]
	s_waitcnt vmcnt(0)
	v_lshlrev_b32_e32 v26, 16, v24
	v_and_b32_e32 v27, 0xffff0000, v24
	v_lshlrev_b32_e32 v24, 16, v25
	v_and_b32_e32 v25, 0xffff0000, v25
	v_lshlrev_b32_e32 v52, 16, v42
	v_and_b32_e32 v53, 0xffff0000, v42
	v_lshlrev_b32_e32 v42, 16, v43
	v_and_b32_e32 v43, 0xffff0000, v43
	v_sub_f32_e32 v9, v9, v27
	v_sub_f32_e32 v8, v8, v26
	v_sub_f32_e32 v11, v11, v25
	v_sub_f32_e32 v10, v10, v24
	v_pk_fma_f32 v[24:25], v[14:15], v[10:11], v[24:25]
	v_pk_fma_f32 v[26:27], v[12:13], v[8:9], v[26:27]
	v_sub_f32_e32 v9, v17, v53
	v_sub_f32_e32 v8, v16, v52
	v_sub_f32_e32 v11, v19, v43
	v_sub_f32_e32 v10, v18, v42
	v_pk_fma_f32 v[10:11], v[32:33], v[10:11], v[42:43]
	v_pk_fma_f32 v[12:13], v[30:31], v[8:9], v[52:53]
	v_pk_mul_f32 v[30:31], v[36:37], v[10:11]
	v_pk_mul_f32 v[14:15], v[34:35], v[12:13]
	v_pk_mul_f32 v[8:9], v[30:31], v[30:31]
	v_pk_mul_f32 v[32:33], v[14:15], v[14:15]
	v_lshlrev_b32_e32 v18, 16, v44
	v_pk_mov_b32 v[42:43], v[32:33], v[8:9] op_sel:[1,0]
	v_mov_b32_e32 v33, v9
	v_pk_add_f32 v[32:33], v[42:43], v[32:33]
	v_and_b32_e32 v19, 0xffff0000, v44
	v_add_f32_e32 v21, v32, v33
	v_lshlrev_b32_e32 v16, 16, v45
	v_and_b32_e32 v17, 0xffff0000, v45
	v_add_f32_dpp v21, v21, v21 quad_perm:[1,0,3,2] row_mask:0xf bank_mask:0xf bound_ctrl:1
	v_pk_add_f32 v[34:35], v[16:17], -1.0 op_sel_hi:[1,0]
	v_pk_add_f32 v[36:37], v[18:19], -1.0 op_sel_hi:[1,0]
	v_add_f32_dpp v21, v21, v21 quad_perm:[2,3,0,1] row_mask:0xf bank_mask:0xf bound_ctrl:1
	v_pk_fma_f32 v[36:37], v[38:39], v[36:37], 1.0 op_sel_hi:[1,1,0]
	v_pk_fma_f32 v[8:9], v[40:41], v[34:35], 1.0 op_sel_hi:[1,1,0]
	v_add_f32_dpp v21, v21, v21 row_half_mirror row_mask:0xf bank_mask:0xf bound_ctrl:1
	v_pk_mul_f32 v[8:9], v[10:11], v[8:9]
	v_pk_mul_f32 v[10:11], v[12:13], v[36:37]
	v_add_f32_dpp v21, v21, v21 row_mirror row_mask:0xf bank_mask:0xf bound_ctrl:1
	v_mov_b32_e32 v32, v10
	v_mov_b32_e32 v34, v8
	s_nop 0
	v_sqrt_f32_e32 v12, v21
	s_nop 0
	v_max_f32_e32 v12, 0x2b8cbccc, v12
	s_nop 0
	v_rcp_f32_e32 v36, v12
	s_nop 0
	v_pk_mul_f32 v[12:13], v[30:31], v[36:37] op_sel_hi:[1,0]
	v_pk_mul_f32 v[14:15], v[14:15], v[36:37] op_sel_hi:[1,0]
	v_pk_mul_f32 v[16:17], v[12:13], v[16:17]
	v_pk_mul_f32 v[18:19], v[14:15], v[18:19]
	v_mov_b32_e32 v35, v17
	v_mov_b32_e32 v33, v19
	v_pk_mov_b32 v[30:31], v[10:11], v[18:19] op_sel:[1,0]
	v_pk_mov_b32 v[36:37], v[8:9], v[16:17] op_sel:[1,0]
	v_pk_mul_f32 v[32:33], v[26:27], v[32:33]
	v_pk_mul_f32 v[34:35], v[24:25], v[34:35]
	v_pk_fma_f32 v[30:31], v[26:27], v[30:31], v[32:33] op_sel:[1,0,0] op_sel_hi:[0,1,1]
	v_pk_fma_f32 v[32:33], v[24:25], v[36:37], v[34:35] op_sel:[1,0,0] op_sel_hi:[0,1,1]
	v_pk_add_f32 v[30:31], v[30:31], v[32:33]
	s_nop 1
	v_mov_b32_dpp v33, v31 quad_perm:[1,0,3,2] row_mask:0xf bank_mask:0xf bound_ctrl:1
	v_mov_b32_dpp v32, v30 quad_perm:[1,0,3,2] row_mask:0xf bank_mask:0xf bound_ctrl:1
	v_pk_add_f32 v[30:31], v[30:31], v[32:33]
	s_nop 1
	v_mov_b32_dpp v33, v31 quad_perm:[2,3,0,1] row_mask:0xf bank_mask:0xf bound_ctrl:1
	v_mov_b32_dpp v32, v30 quad_perm:[2,3,0,1] row_mask:0xf bank_mask:0xf bound_ctrl:1
	v_pk_add_f32 v[30:31], v[30:31], v[32:33]
	s_nop 1
	v_mov_b32_dpp v33, v31 row_half_mirror row_mask:0xf bank_mask:0xf bound_ctrl:1
	v_mov_b32_dpp v32, v30 row_half_mirror row_mask:0xf bank_mask:0xf bound_ctrl:1
	v_pk_add_f32 v[30:31], v[30:31], v[32:33]
	s_nop 1
	v_mov_b32_dpp v33, v31 row_mirror row_mask:0xf bank_mask:0xf bound_ctrl:1
	v_mov_b32_dpp v32, v30 row_mirror row_mask:0xf bank_mask:0xf bound_ctrl:1
	s_and_saveexec_b64 s[0:1], s[2:3]
	s_cbranch_execz .LBB0_1031
	v_mov_b32_e32 v21, v1
	v_lshl_add_u64 v[20:21], s[28:29], 0, v[20:21]
	v_add_co_u32_e32 v20, vcc, 0x1000, v20
	v_lshl_add_u64 v[34:35], v[0:1], 2, s[24:25]
	s_nop 0
	v_addc_co_u32_e32 v21, vcc, 0, v21, vcc
	global_load_dwordx2 v[38:39], v[20:21], off
	v_add_co_u32_e32 v20, vcc, 0x2000, v22
	global_load_dwordx4 v[34:37], v[34:35], off
	s_nop 0
	v_addc_co_u32_e32 v21, vcc, 0, v23, vcc
	global_load_dwordx4 v[20:23], v[20:21], off
	s_waitcnt vmcnt(2)
	v_lshlrev_b32_e32 v40, 16, v38
	v_and_b32_e32 v41, 0xffff0000, v38
	v_lshlrev_b32_e32 v38, 16, v39
	v_and_b32_e32 v39, 0xffff0000, v39
	s_waitcnt vmcnt(0)
	v_sub_f32_e32 v21, v21, v41
	v_sub_f32_e32 v20, v20, v40
	v_sub_f32_e32 v23, v23, v39
	v_sub_f32_e32 v22, v22, v38
	v_pk_fma_f32 v[22:23], v[36:37], v[22:23], v[38:39]
	v_pk_fma_f32 v[20:21], v[34:35], v[20:21], v[40:41]
	ds_write_b128 v47, v[20:23] offset:1280

; __device__ __forceinline__ float softplus_(float x) { return x > 20.f ? x : log1pf(expf(x)); }
; template <int ph>
; __device__ __forceinline__ void run_phase(const Args& args, LAS unsigned char* lds, const int G, const int bx, const bool fin = true) {
;     ...
;                 const int b = unit >> 4, l8 = tid & 7, ch = (unit & 15) * 64 + 8 * l8, seg = tid >> 3, t0 = seg * 32;
;                 const f32x4 lam0 = *(const f32x4*)(lru_lambda + ch), lam1 = *(const f32x4*)(lru_lambda + ch + 4);
;                 const f32x4 sp0 = (f32x4){softplus_(-lam0[0]), softplus_(-lam0[1]), softplus_(-lam0[2]), softplus_(-lam0[3])} * -8.0f,
;                             sp1 = (f32x4){softplus_(-lam1[0]), softplus_(-lam1[1]), softplus_(-lam1[2]), softplus_(-lam1[3])} * -8.0f;
.LBB0_1044:
	s_lshl_b32 s0, s78, 6
	s_and_b32 s0, s0, 0x3c0
	v_or_b32_e32 v1, s0, v52
	v_readlane_b32 s8, v229, 48
	v_lshlrev_b32_e32 v60, 2, v1
	v_readlane_b32 s10, v229, 50
	v_readlane_b32 s11, v229, 51
	s_nop 4
	global_load_dwordx4 v[6:9], v60, s[10:11]
	global_load_dwordx4 v[2:5], v60, s[10:11] offset:16
	v_readlane_b32 s9, v229, 49
	v_readlane_b32 s12, v229, 52
	v_readlane_b32 s13, v229, 53
	v_readlane_b32 s14, v229, 54
	v_readlane_b32 s15, v229, 55
	v_readlane_b32 s16, v229, 56
	v_readlane_b32 s17, v229, 57
	v_readlane_b32 s18, v229, 58
	v_readlane_b32 s19, v229, 59
	v_readlane_b32 s20, v229, 60
	v_readlane_b32 s21, v229, 61
	v_readlane_b32 s22, v229, 62
	v_readlane_b32 s23, v229, 63
	s_waitcnt vmcnt(1)
	v_xor_b32_e32 v10, 0x80000000, v6
	v_cmp_ngt_f32_e32 vcc, s38, v6
	s_and_saveexec_b64 s[0:1], vcc
	s_cbranch_execz .LBB0_1046
	v_mul_f32_e32 v1, 0xbfb8aa3b, v6
	v_rndne_f32_e32 v10, v1
	v_sub_f32_e32 v11, v1, v10
	v_fma_f32 v1, v6, s39, -v1
	v_fmac_f32_e32 v1, 0xb2a5705f, v6
	v_add_f32_e32 v1, v11, v1
	v_cvt_i32_f32_e32 v10, v10
	v_exp_f32_e32 v1, v1
	v_cmp_nlt_f32_e32 vcc, s40, v6
	v_ldexp_f32 v1, v1, v10
	s_nop 0
	v_cndmask_b32_e32 v1, 0, v1, vcc
	v_cmp_ngt_f32_e32 vcc, s41, v6
	s_nop 1
	v_cndmask_b32_e32 v1, v59, v1, vcc
	v_add_f32_e32 v6, 1.0, v1
	v_add_f32_e32 v10, -1.0, v6
	v_sub_f32_e32 v11, v10, v6
	v_add_f32_e32 v11, 1.0, v11
	v_sub_f32_e32 v10, v1, v10
	v_add_f32_e32 v12, v10, v11
	v_frexp_mant_f32_e32 v13, v6
	v_cvt_f64_f32_e32 v[10:11], v6
	v_frexp_exp_i32_f64_e32 v10, v[10:11]
	v_cmp_gt_f32_e32 vcc, s43, v13
	s_nop 1
	v_subbrev_co_u32_e32 v18, vcc, 0, v10, vcc
	v_sub_u32_e32 v10, 0, v18
	v_ldexp_f32 v6, v6, v10
	v_ldexp_f32 v10, v12, v10
	v_add_f32_e32 v12, -1.0, v6
	v_add_f32_e32 v11, 1.0, v12
	v_sub_f32_e32 v11, v6, v11
	v_add_f32_e32 v13, v10, v11
	v_add_f32_e32 v11, 1.0, v6
	v_add_f32_e32 v14, -1.0, v11
	v_sub_f32_e32 v6, v6, v14
	v_add_f32_e32 v6, v10, v6
	v_add_f32_e32 v19, v11, v6
	s_nop 0
	v_rcp_f32_e32 v20, v19
	v_sub_f32_e32 v10, v11, v19
	v_add_f32_e32 v11, v12, v13
	v_add_f32_e32 v6, v6, v10
	v_mul_f32_e32 v25, v11, v20
	v_sub_f32_e32 v10, v12, v11
	v_mul_f32_e32 v12, v19, v25
	v_fma_f32 v14, v25, v19, -v12
	v_fmac_f32_e32 v14, v25, v6
	v_add_f32_e32 v21, v13, v10
	v_add_f32_e32 v10, v12, v14
	v_sub_f32_e32 v13, v11, v10
	v_pk_add_f32 v[16:17], v[10:11], v[12:13] neg_lo:[0,1] neg_hi:[0,1]
	v_mov_b32_e32 v15, v10
	v_pk_add_f32 v[10:11], v[16:17], v[14:15] neg_lo:[0,1] neg_hi:[0,1]
	v_cmp_neq_f32_e32 vcc, s42, v1
	v_add_f32_e32 v11, v21, v11
	v_add_f32_e32 v10, v10, v11
	v_add_f32_e32 v11, v13, v10
	v_mul_f32_e32 v21, v20, v11
	v_mul_f32_e32 v12, v19, v21
	v_fma_f32 v14, v21, v19, -v12
	v_fmac_f32_e32 v14, v21, v6
	v_sub_f32_e32 v6, v13, v11
	v_add_f32_e32 v6, v10, v6
	v_add_f32_e32 v10, v12, v14
	v_sub_f32_e32 v13, v11, v10
	v_pk_add_f32 v[16:17], v[10:11], v[12:13] neg_lo:[0,1] neg_hi:[0,1]
	v_mov_b32_e32 v15, v10
	v_pk_add_f32 v[10:11], v[16:17], v[14:15] neg_lo:[0,1] neg_hi:[0,1]
	s_nop 0
	v_add_f32_e32 v6, v6, v11
	v_add_f32_e32 v6, v10, v6
	v_add_f32_e32 v11, v25, v21
	v_add_f32_e32 v6, v13, v6
	v_sub_f32_e32 v10, v11, v25
	v_mul_f32_e32 v6, v20, v6
	v_sub_f32_e32 v10, v21, v10
	v_add_f32_e32 v6, v10, v6
	v_add_f32_e32 v12, v11, v6
	v_mul_f32_e32 v14, v12, v12
	v_fmamk_f32 v10, v14, 0x3e9b6dac, v57
	v_fmaak_f32 v25, v14, v10, 0x3f2aaada
	v_cvt_f32_i32_e32 v10, v18
	v_sub_f32_e32 v11, v12, v11
	v_sub_f32_e32 v6, v6, v11
	v_mul_f32_e32 v11, v12, v14
	v_pk_mul_f32 v[14:15], v[10:11], v[24:25]
	v_ldexp_f32 v13, v12, 1
	v_fma_f32 v12, v10, s44, -v14
	v_fmac_f32_e32 v12, 0xb102e308, v10
	v_pk_add_f32 v[10:11], v[14:15], v[12:13]
	v_ldexp_f32 v6, v6, 1
	v_sub_f32_e32 v13, v11, v13
	v_sub_f32_e32 v13, v15, v13
	v_add_f32_e32 v17, v6, v13
	v_mov_b32_e32 v16, v14
	v_pk_add_f32 v[14:15], v[10:11], v[14:15] neg_lo:[0,1] neg_hi:[0,1]
	v_pk_add_f32 v[18:19], v[10:11], v[16:17]
	v_mov_b32_e32 v13, v10
	v_mov_b32_e32 v15, v19
	v_pk_add_f32 v[20:21], v[12:13], v[14:15] neg_lo:[0,1] neg_hi:[0,1]
	v_pk_add_f32 v[12:13], v[12:13], v[14:15]
	v_mov_b32_e32 v16, v17
	v_pk_add_f32 v[14:15], v[12:13], v[10:11] op_sel:[1,0] op_sel_hi:[0,1] neg_lo:[0,1] neg_hi:[0,1]
	v_pk_add_f32 v[26:27], v[18:19], v[14:15] op_sel_hi:[1,0] neg_lo:[0,1] neg_hi:[0,1]
	v_mov_b32_e32 v18, v19
	v_mov_b32_e32 v19, v13
	v_pk_mov_b32 v[14:15], v[10:11], v[14:15] op_sel:[1,0]
	v_mov_b32_e32 v17, v10
	v_pk_add_f32 v[14:15], v[18:19], v[14:15] neg_lo:[0,1] neg_hi:[0,1]
	v_mov_b32_e32 v26, v20
	v_pk_add_f32 v[10:11], v[16:17], v[14:15] neg_lo:[0,1] neg_hi:[0,1]
	v_mov_b32_e32 v21, v13
	v_pk_add_f32 v[14:15], v[26:27], v[10:11]
	s_nop 0
	v_pk_add_f32 v[16:17], v[14:15], v[14:15] op_sel:[0,1] op_sel_hi:[1,0]
	s_nop 0
	v_pk_add_f32 v[12:13], v[12:13], v[16:17] op_sel:[1,0] op_sel_hi:[0,1]
	v_mov_b32_e32 v15, v12
	v_pk_add_f32 v[18:19], v[14:15], v[20:21] neg_lo:[0,1] neg_hi:[0,1]
	v_mov_b32_e32 v11, v16
	v_sub_f32_e32 v6, v14, v18
	v_pk_add_f32 v[10:11], v[10:11], v[18:19] neg_lo:[0,1] neg_hi:[0,1]
	v_sub_f32_e32 v6, v20, v6
	v_add_f32_e32 v6, v10, v6
	v_add_f32_e32 v6, v6, v11
	v_add_f32_e32 v6, v12, v6
	v_cndmask_b32_e32 v6, v59, v6, vcc
	v_cmp_lt_f32_e64 vcc, |v1|, s45
	s_nop 1
	v_cndmask_b32_e32 v10, v6, v1, vcc
; __device__ __forceinline__ float softplus_(float x) { return x > 20.f ? x : log1pf(expf(x)); }
; template <int ph>
; __device__ __forceinline__ void run_phase(const Args& args, LAS unsigned char* lds, const int G, const int bx, const bool fin = true) {
;     ...
;                 const f32x4 lam0 = *(const f32x4*)(lru_lambda + ch), lam1 = *(const f32x4*)(lru_lambda + ch + 4);
;                 const f32x4 sp0 = (f32x4){softplus_(-lam0[0]), softplus_(-lam0[1]), softplus_(-lam0[2]), softplus_(-lam0[3])} * -8.0f,
;                             sp1 = (f32x4){softplus_(-lam1[0]), softplus_(-lam1[1]), softplus_(-lam1[2]), softplus_(-lam1[3])} * -8.0f;
.LBB0_1046:
	s_or_b64 exec, exec, s[0:1]
	v_xor_b32_e32 v11, 0x80000000, v7
	v_cmp_ngt_f32_e32 vcc, s38, v7
	s_and_saveexec_b64 s[0:1], vcc
	s_cbranch_execz .LBB0_1048
	v_mul_f32_e32 v1, 0xbfb8aa3b, v7
	v_rndne_f32_e32 v6, v1
	v_sub_f32_e32 v11, v1, v6
	v_fma_f32 v1, v7, s39, -v1
	v_fmac_f32_e32 v1, 0xb2a5705f, v7
	v_add_f32_e32 v1, v11, v1
	v_cvt_i32_f32_e32 v6, v6
	v_exp_f32_e32 v1, v1
	v_cmp_nlt_f32_e32 vcc, s40, v7
	v_ldexp_f32 v1, v1, v6
	s_nop 0
	v_cndmask_b32_e32 v1, 0, v1, vcc
	v_cmp_ngt_f32_e32 vcc, s41, v7
	s_nop 1
	v_cndmask_b32_e32 v1, v59, v1, vcc
	v_add_f32_e32 v11, 1.0, v1
	v_add_f32_e32 v6, -1.0, v11
	v_sub_f32_e32 v7, v6, v11
	v_add_f32_e32 v7, 1.0, v7
	v_sub_f32_e32 v6, v1, v6
	v_add_f32_e32 v12, v6, v7
	v_frexp_mant_f32_e32 v13, v11
	v_cvt_f64_f32_e32 v[6:7], v11
	v_frexp_exp_i32_f64_e32 v6, v[6:7]
	v_cmp_gt_f32_e32 vcc, s43, v13
	s_nop 1
	v_subbrev_co_u32_e32 v18, vcc, 0, v6, vcc
	v_sub_u32_e32 v6, 0, v18
	v_ldexp_f32 v7, v11, v6
	v_add_f32_e32 v11, -1.0, v7
	v_add_f32_e32 v13, 1.0, v7
	v_ldexp_f32 v6, v12, v6
	v_add_f32_e32 v12, 1.0, v11
	v_add_f32_e32 v14, -1.0, v13
	v_sub_f32_e32 v12, v7, v12
	v_sub_f32_e32 v7, v7, v14
	v_add_f32_e32 v12, v6, v12
	v_add_f32_e32 v6, v6, v7
	v_add_f32_e32 v19, v13, v6
	s_nop 0
	v_rcp_f32_e32 v21, v19
	v_sub_f32_e32 v7, v13, v19
	v_add_f32_e32 v20, v6, v7
	v_add_f32_e32 v7, v11, v12
	v_sub_f32_e32 v6, v11, v7
	v_mul_f32_e32 v25, v7, v21
	v_add_f32_e32 v11, v12, v6
	v_mul_f32_e32 v12, v19, v25
	v_fma_f32 v14, v25, v19, -v12
	v_fmac_f32_e32 v14, v25, v20
	v_add_f32_e32 v6, v12, v14
	v_sub_f32_e32 v13, v7, v6
	v_pk_add_f32 v[16:17], v[6:7], v[12:13] neg_lo:[0,1] neg_hi:[0,1]
	v_mov_b32_e32 v15, v6
	v_pk_add_f32 v[6:7], v[16:17], v[14:15] neg_lo:[0,1] neg_hi:[0,1]
	v_cmp_neq_f32_e32 vcc, s42, v1
	v_add_f32_e32 v7, v11, v7
	v_add_f32_e32 v6, v6, v7
	v_add_f32_e32 v7, v13, v6
	v_mul_f32_e32 v11, v21, v7
	v_mul_f32_e32 v12, v19, v11
	v_fma_f32 v14, v11, v19, -v12
	v_fmac_f32_e32 v14, v11, v20
	v_sub_f32_e32 v13, v13, v7
	v_add_f32_e32 v19, v6, v13
	v_add_f32_e32 v6, v12, v14
	v_sub_f32_e32 v13, v7, v6
	v_pk_add_f32 v[16:17], v[6:7], v[12:13] neg_lo:[0,1] neg_hi:[0,1]
	v_mov_b32_e32 v15, v6
	v_pk_add_f32 v[6:7], v[16:17], v[14:15] neg_lo:[0,1] neg_hi:[0,1]
	s_nop 0
	v_add_f32_e32 v7, v19, v7
	v_add_f32_e32 v6, v6, v7
	v_add_f32_e32 v7, v25, v11
	v_add_f32_e32 v6, v13, v6
	v_sub_f32_e32 v12, v7, v25
	v_mul_f32_e32 v6, v21, v6
	v_sub_f32_e32 v11, v11, v12
	v_add_f32_e32 v11, v11, v6
	v_add_f32_e32 v12, v7, v11
	v_mul_f32_e32 v14, v12, v12
	v_fmamk_f32 v6, v14, 0x3e9b6dac, v57
	v_fmaak_f32 v25, v14, v6, 0x3f2aaada
	v_cvt_f32_i32_e32 v6, v18
	v_sub_f32_e32 v7, v12, v7
	v_sub_f32_e32 v7, v11, v7
	v_ldexp_f32 v11, v7, 1
	v_mul_f32_e32 v7, v12, v14
	v_pk_mul_f32 v[14:15], v[6:7], v[24:25]
	v_ldexp_f32 v13, v12, 1
	v_fma_f32 v12, v6, s44, -v14
	v_fmac_f32_e32 v12, 0xb102e308, v6
	v_pk_add_f32 v[6:7], v[14:15], v[12:13]
	v_mov_b32_e32 v16, v14
	v_sub_f32_e32 v13, v7, v13
	v_sub_f32_e32 v13, v15, v13
	v_add_f32_e32 v17, v11, v13
	v_pk_add_f32 v[14:15], v[6:7], v[14:15] neg_lo:[0,1] neg_hi:[0,1]
	v_pk_add_f32 v[18:19], v[6:7], v[16:17]
	v_mov_b32_e32 v13, v6
	v_mov_b32_e32 v15, v19
	v_pk_add_f32 v[20:21], v[12:13], v[14:15] neg_lo:[0,1] neg_hi:[0,1]
	v_pk_add_f32 v[12:13], v[12:13], v[14:15]
	v_mov_b32_e32 v16, v17
	v_pk_add_f32 v[14:15], v[12:13], v[6:7] op_sel:[1,0] op_sel_hi:[0,1] neg_lo:[0,1] neg_hi:[0,1]
	v_pk_add_f32 v[26:27], v[18:19], v[14:15] op_sel_hi:[1,0] neg_lo:[0,1] neg_hi:[0,1]
	v_mov_b32_e32 v18, v19
	v_mov_b32_e32 v19, v13
	v_pk_mov_b32 v[14:15], v[6:7], v[14:15] op_sel:[1,0]
	v_mov_b32_e32 v17, v6
	v_pk_add_f32 v[14:15], v[18:19], v[14:15] neg_lo:[0,1] neg_hi:[0,1]
	v_mov_b32_e32 v26, v20
	v_pk_add_f32 v[6:7], v[16:17], v[14:15] neg_lo:[0,1] neg_hi:[0,1]
	v_mov_b32_e32 v21, v13
	v_pk_add_f32 v[14:15], v[26:27], v[6:7]
	s_nop 0
	v_pk_add_f32 v[16:17], v[14:15], v[14:15] op_sel:[0,1] op_sel_hi:[1,0]
	s_nop 0
	v_pk_add_f32 v[12:13], v[12:13], v[16:17] op_sel:[1,0] op_sel_hi:[0,1]
	v_mov_b32_e32 v15, v12
	v_pk_add_f32 v[18:19], v[14:15], v[20:21] neg_lo:[0,1] neg_hi:[0,1]
	v_mov_b32_e32 v7, v16
	v_sub_f32_e32 v11, v14, v18
	v_pk_add_f32 v[6:7], v[6:7], v[18:19] neg_lo:[0,1] neg_hi:[0,1]
	v_sub_f32_e32 v11, v20, v11
	v_add_f32_e32 v6, v6, v11
	v_add_f32_e32 v6, v6, v7
	v_add_f32_e32 v6, v12, v6
	v_cndmask_b32_e32 v6, v59, v6, vcc
	v_cmp_lt_f32_e64 vcc, |v1|, s45
	s_nop 1
	v_cndmask_b32_e32 v11, v6, v1, vcc
; __device__ __forceinline__ float softplus_(float x) { return x > 20.f ? x : log1pf(expf(x)); }
; template <int ph>
; __device__ __forceinline__ void run_phase(const Args& args, LAS unsigned char* lds, const int G, const int bx, const bool fin = true) {
;     ...
;                 const f32x4 lam0 = *(const f32x4*)(lru_lambda + ch), lam1 = *(const f32x4*)(lru_lambda + ch + 4);
;                 const f32x4 sp0 = (f32x4){softplus_(-lam0[0]), softplus_(-lam0[1]), softplus_(-lam0[2]), softplus_(-lam0[3])} * -8.0f,
;                             sp1 = (f32x4){softplus_(-lam1[0]), softplus_(-lam1[1]), softplus_(-lam1[2]), softplus_(-lam1[3])} * -8.0f;
.LBB0_1048:
	s_or_b64 exec, exec, s[0:1]
	v_xor_b32_e32 v6, 0x80000000, v8
	v_cmp_ngt_f32_e32 vcc, s38, v8
	s_and_saveexec_b64 s[0:1], vcc
	s_cbranch_execz .LBB0_1050
	v_mul_f32_e32 v1, 0xbfb8aa3b, v8
	v_rndne_f32_e32 v6, v1
	v_sub_f32_e32 v7, v1, v6
	v_fma_f32 v1, v8, s39, -v1
	v_fmac_f32_e32 v1, 0xb2a5705f, v8
	v_add_f32_e32 v1, v7, v1
	v_cvt_i32_f32_e32 v6, v6
	v_exp_f32_e32 v1, v1
	v_cmp_nlt_f32_e32 vcc, s40, v8
	v_ldexp_f32 v1, v1, v6
	s_nop 0
	v_cndmask_b32_e32 v1, 0, v1, vcc
	v_cmp_ngt_f32_e32 vcc, s41, v8
	s_nop 1
	v_cndmask_b32_e32 v1, v59, v1, vcc
	v_add_f32_e32 v8, 1.0, v1
	v_add_f32_e32 v6, -1.0, v8
	v_sub_f32_e32 v7, v6, v8
	v_add_f32_e32 v7, 1.0, v7
	v_sub_f32_e32 v6, v1, v6
	v_add_f32_e32 v12, v6, v7
	v_frexp_mant_f32_e32 v13, v8
	v_cvt_f64_f32_e32 v[6:7], v8
	v_frexp_exp_i32_f64_e32 v6, v[6:7]
	v_cmp_gt_f32_e32 vcc, s43, v13
	s_nop 1
	v_subbrev_co_u32_e32 v18, vcc, 0, v6, vcc
	v_sub_u32_e32 v6, 0, v18
	v_ldexp_f32 v7, v8, v6
	v_add_f32_e32 v8, -1.0, v7
	v_add_f32_e32 v13, 1.0, v7
	v_ldexp_f32 v6, v12, v6
	v_add_f32_e32 v12, 1.0, v8
	v_add_f32_e32 v14, -1.0, v13
	v_sub_f32_e32 v12, v7, v12
	v_sub_f32_e32 v7, v7, v14
	v_add_f32_e32 v12, v6, v12
	v_add_f32_e32 v6, v6, v7
	v_add_f32_e32 v19, v13, v6
	s_nop 0
	v_rcp_f32_e32 v21, v19
	v_sub_f32_e32 v7, v13, v19
	v_add_f32_e32 v20, v6, v7
	v_add_f32_e32 v7, v8, v12
	v_sub_f32_e32 v6, v8, v7
	v_mul_f32_e32 v25, v7, v21
	v_add_f32_e32 v8, v12, v6
	v_mul_f32_e32 v12, v19, v25
	v_fma_f32 v14, v25, v19, -v12
	v_fmac_f32_e32 v14, v25, v20
	v_add_f32_e32 v6, v12, v14
	v_sub_f32_e32 v13, v7, v6
	v_pk_add_f32 v[16:17], v[6:7], v[12:13] neg_lo:[0,1] neg_hi:[0,1]
	v_mov_b32_e32 v15, v6
	v_pk_add_f32 v[6:7], v[16:17], v[14:15] neg_lo:[0,1] neg_hi:[0,1]
	v_cmp_neq_f32_e32 vcc, s42, v1
	v_add_f32_e32 v7, v8, v7
	v_add_f32_e32 v6, v6, v7
	v_add_f32_e32 v7, v13, v6
	v_mul_f32_e32 v8, v21, v7
	v_mul_f32_e32 v12, v19, v8
	v_fma_f32 v14, v8, v19, -v12
	v_fmac_f32_e32 v14, v8, v20
	v_sub_f32_e32 v13, v13, v7
	v_add_f32_e32 v19, v6, v13
	v_add_f32_e32 v6, v12, v14
	v_sub_f32_e32 v13, v7, v6
	v_pk_add_f32 v[16:17], v[6:7], v[12:13] neg_lo:[0,1] neg_hi:[0,1]
	v_mov_b32_e32 v15, v6
	v_pk_add_f32 v[6:7], v[16:17], v[14:15] neg_lo:[0,1] neg_hi:[0,1]
	s_nop 0
	v_add_f32_e32 v7, v19, v7
	v_add_f32_e32 v6, v6, v7
	v_add_f32_e32 v7, v25, v8
	v_add_f32_e32 v6, v13, v6
	v_sub_f32_e32 v12, v7, v25
	v_mul_f32_e32 v6, v21, v6
	v_sub_f32_e32 v8, v8, v12
	v_add_f32_e32 v8, v8, v6
	v_add_f32_e32 v12, v7, v8
	v_mul_f32_e32 v14, v12, v12
	v_fmamk_f32 v6, v14, 0x3e9b6dac, v57
	v_fmaak_f32 v25, v14, v6, 0x3f2aaada
	v_cvt_f32_i32_e32 v6, v18
	v_sub_f32_e32 v7, v12, v7
	v_sub_f32_e32 v7, v8, v7
	v_ldexp_f32 v8, v7, 1
	v_mul_f32_e32 v7, v12, v14
	v_pk_mul_f32 v[14:15], v[6:7], v[24:25]
	v_ldexp_f32 v13, v12, 1
	v_fma_f32 v12, v6, s44, -v14
	v_fmac_f32_e32 v12, 0xb102e308, v6
	v_pk_add_f32 v[6:7], v[14:15], v[12:13]
	v_mov_b32_e32 v16, v14
	v_sub_f32_e32 v13, v7, v13
	v_sub_f32_e32 v13, v15, v13
	v_add_f32_e32 v17, v8, v13
	v_pk_add_f32 v[14:15], v[6:7], v[14:15] neg_lo:[0,1] neg_hi:[0,1]
	v_pk_add_f32 v[18:19], v[6:7], v[16:17]
	v_mov_b32_e32 v13, v6
	v_mov_b32_e32 v15, v19
	v_pk_add_f32 v[20:21], v[12:13], v[14:15] neg_lo:[0,1] neg_hi:[0,1]
	v_pk_add_f32 v[12:13], v[12:13], v[14:15]
	v_mov_b32_e32 v16, v17
	v_pk_add_f32 v[14:15], v[12:13], v[6:7] op_sel:[1,0] op_sel_hi:[0,1] neg_lo:[0,1] neg_hi:[0,1]
	v_pk_add_f32 v[26:27], v[18:19], v[14:15] op_sel_hi:[1,0] neg_lo:[0,1] neg_hi:[0,1]
	v_mov_b32_e32 v18, v19
	v_mov_b32_e32 v19, v13
	v_pk_mov_b32 v[14:15], v[6:7], v[14:15] op_sel:[1,0]
	v_mov_b32_e32 v17, v6
	v_pk_add_f32 v[14:15], v[18:19], v[14:15] neg_lo:[0,1] neg_hi:[0,1]
	v_mov_b32_e32 v26, v20
	v_pk_add_f32 v[6:7], v[16:17], v[14:15] neg_lo:[0,1] neg_hi:[0,1]
	v_mov_b32_e32 v21, v13
	v_pk_add_f32 v[14:15], v[26:27], v[6:7]
	s_nop 0
	v_pk_add_f32 v[16:17], v[14:15], v[14:15] op_sel:[0,1] op_sel_hi:[1,0]
	s_nop 0
	v_pk_add_f32 v[12:13], v[12:13], v[16:17] op_sel:[1,0] op_sel_hi:[0,1]
	v_mov_b32_e32 v15, v12
	v_pk_add_f32 v[18:19], v[14:15], v[20:21] neg_lo:[0,1] neg_hi:[0,1]
	v_mov_b32_e32 v7, v16
	v_sub_f32_e32 v8, v14, v18
	v_pk_add_f32 v[6:7], v[6:7], v[18:19] neg_lo:[0,1] neg_hi:[0,1]
	v_sub_f32_e32 v8, v20, v8
	v_add_f32_e32 v6, v6, v8
	v_add_f32_e32 v6, v6, v7
	v_add_f32_e32 v6, v12, v6
	v_cndmask_b32_e32 v6, v59, v6, vcc
	v_cmp_lt_f32_e64 vcc, |v1|, s45
	s_nop 1
	v_cndmask_b32_e32 v6, v6, v1, vcc
; __device__ __forceinline__ float softplus_(float x) { return x > 20.f ? x : log1pf(expf(x)); }
; template <int ph>
; __device__ __forceinline__ void run_phase(const Args& args, LAS unsigned char* lds, const int G, const int bx, const bool fin = true) {
;     ...
;                 const f32x4 lam0 = *(const f32x4*)(lru_lambda + ch), lam1 = *(const f32x4*)(lru_lambda + ch + 4);
;                 const f32x4 sp0 = (f32x4){softplus_(-lam0[0]), softplus_(-lam0[1]), softplus_(-lam0[2]), softplus_(-lam0[3])} * -8.0f,
;                             sp1 = (f32x4){softplus_(-lam1[0]), softplus_(-lam1[1]), softplus_(-lam1[2]), softplus_(-lam1[3])} * -8.0f;
.LBB0_1050:
	s_or_b64 exec, exec, s[0:1]
	v_xor_b32_e32 v7, 0x80000000, v9
	v_cmp_ngt_f32_e32 vcc, s38, v9
	s_and_saveexec_b64 s[0:1], vcc
	s_cbranch_execz .LBB0_1052
	v_mul_f32_e32 v1, 0xbfb8aa3b, v9
	v_rndne_f32_e32 v7, v1
	v_sub_f32_e32 v8, v1, v7
	v_fma_f32 v1, v9, s39, -v1
	v_fmac_f32_e32 v1, 0xb2a5705f, v9
	v_add_f32_e32 v1, v8, v1
	v_cvt_i32_f32_e32 v7, v7
	v_exp_f32_e32 v1, v1
	v_cmp_nlt_f32_e32 vcc, s40, v9
	v_ldexp_f32 v1, v1, v7
	s_nop 0
	v_cndmask_b32_e32 v1, 0, v1, vcc
	v_cmp_ngt_f32_e32 vcc, s41, v9
	s_nop 1
	v_cndmask_b32_e32 v1, v59, v1, vcc
	v_add_f32_e32 v7, 1.0, v1
	v_add_f32_e32 v8, -1.0, v7
	v_sub_f32_e32 v9, v8, v7
	v_add_f32_e32 v9, 1.0, v9
	v_sub_f32_e32 v8, v1, v8
	v_add_f32_e32 v12, v8, v9
	v_frexp_mant_f32_e32 v13, v7
	v_cvt_f64_f32_e32 v[8:9], v7
	v_frexp_exp_i32_f64_e32 v8, v[8:9]
	v_cmp_gt_f32_e32 vcc, s43, v13
	s_nop 1
	v_subbrev_co_u32_e32 v18, vcc, 0, v8, vcc
	v_sub_u32_e32 v8, 0, v18
	v_ldexp_f32 v7, v7, v8
	v_ldexp_f32 v8, v12, v8
	v_add_f32_e32 v12, -1.0, v7
	v_add_f32_e32 v9, 1.0, v12
	v_sub_f32_e32 v9, v7, v9
	v_add_f32_e32 v13, v8, v9
	v_add_f32_e32 v9, 1.0, v7
	v_add_f32_e32 v14, -1.0, v9
	v_sub_f32_e32 v7, v7, v14
	v_add_f32_e32 v7, v8, v7
	v_add_f32_e32 v19, v9, v7
	s_nop 0
	v_rcp_f32_e32 v20, v19
	v_sub_f32_e32 v8, v9, v19
	v_add_f32_e32 v9, v12, v13
	v_add_f32_e32 v7, v7, v8
	v_mul_f32_e32 v25, v9, v20
	v_sub_f32_e32 v8, v12, v9
	v_mul_f32_e32 v12, v19, v25
	v_fma_f32 v14, v25, v19, -v12
	v_fmac_f32_e32 v14, v25, v7
	v_add_f32_e32 v21, v13, v8
	v_add_f32_e32 v8, v12, v14
	v_sub_f32_e32 v13, v9, v8
	v_pk_add_f32 v[16:17], v[8:9], v[12:13] neg_lo:[0,1] neg_hi:[0,1]
	v_mov_b32_e32 v15, v8
	v_pk_add_f32 v[8:9], v[16:17], v[14:15] neg_lo:[0,1] neg_hi:[0,1]
	v_cmp_neq_f32_e32 vcc, s42, v1
	v_add_f32_e32 v9, v21, v9
	v_add_f32_e32 v8, v8, v9
	v_add_f32_e32 v9, v13, v8
	v_mul_f32_e32 v21, v20, v9
	v_mul_f32_e32 v12, v19, v21
	v_fma_f32 v14, v21, v19, -v12
	v_fmac_f32_e32 v14, v21, v7
	v_sub_f32_e32 v7, v13, v9
	v_add_f32_e32 v7, v8, v7
	v_add_f32_e32 v8, v12, v14
	v_sub_f32_e32 v13, v9, v8
	v_pk_add_f32 v[16:17], v[8:9], v[12:13] neg_lo:[0,1] neg_hi:[0,1]
	v_mov_b32_e32 v15, v8
	v_pk_add_f32 v[8:9], v[16:17], v[14:15] neg_lo:[0,1] neg_hi:[0,1]
	s_nop 0
	v_add_f32_e32 v7, v7, v9
	v_add_f32_e32 v7, v8, v7
	v_add_f32_e32 v9, v25, v21
	v_add_f32_e32 v7, v13, v7
	v_sub_f32_e32 v8, v9, v25
	v_mul_f32_e32 v7, v20, v7
	v_sub_f32_e32 v8, v21, v8
	v_add_f32_e32 v7, v8, v7
	v_add_f32_e32 v12, v9, v7
	v_mul_f32_e32 v14, v12, v12
	v_fmamk_f32 v8, v14, 0x3e9b6dac, v57
	v_fmaak_f32 v25, v14, v8, 0x3f2aaada
	v_cvt_f32_i32_e32 v8, v18
	v_sub_f32_e32 v9, v12, v9
	v_sub_f32_e32 v7, v7, v9
	v_mul_f32_e32 v9, v12, v14
	v_pk_mul_f32 v[14:15], v[8:9], v[24:25]
	v_ldexp_f32 v13, v12, 1
	v_fma_f32 v12, v8, s44, -v14
	v_fmac_f32_e32 v12, 0xb102e308, v8
	v_pk_add_f32 v[8:9], v[14:15], v[12:13]
	v_ldexp_f32 v7, v7, 1
	v_sub_f32_e32 v13, v9, v13
	v_sub_f32_e32 v13, v15, v13
	v_add_f32_e32 v17, v7, v13
	v_mov_b32_e32 v16, v14
	v_pk_add_f32 v[14:15], v[8:9], v[14:15] neg_lo:[0,1] neg_hi:[0,1]
	v_pk_add_f32 v[18:19], v[8:9], v[16:17]
	v_mov_b32_e32 v13, v8
	v_mov_b32_e32 v15, v19
	v_pk_add_f32 v[20:21], v[12:13], v[14:15] neg_lo:[0,1] neg_hi:[0,1]
	v_pk_add_f32 v[12:13], v[12:13], v[14:15]
	v_mov_b32_e32 v16, v17
	v_pk_add_f32 v[14:15], v[12:13], v[8:9] op_sel:[1,0] op_sel_hi:[0,1] neg_lo:[0,1] neg_hi:[0,1]
	v_pk_add_f32 v[26:27], v[18:19], v[14:15] op_sel_hi:[1,0] neg_lo:[0,1] neg_hi:[0,1]
	v_mov_b32_e32 v18, v19
	v_mov_b32_e32 v19, v13
	v_pk_mov_b32 v[14:15], v[8:9], v[14:15] op_sel:[1,0]
	v_mov_b32_e32 v17, v8
	v_pk_add_f32 v[14:15], v[18:19], v[14:15] neg_lo:[0,1] neg_hi:[0,1]
	v_mov_b32_e32 v26, v20
	v_pk_add_f32 v[8:9], v[16:17], v[14:15] neg_lo:[0,1] neg_hi:[0,1]
	v_mov_b32_e32 v21, v13
	v_pk_add_f32 v[14:15], v[26:27], v[8:9]
	s_nop 0
	v_pk_add_f32 v[16:17], v[14:15], v[14:15] op_sel:[0,1] op_sel_hi:[1,0]
	s_nop 0
	v_pk_add_f32 v[12:13], v[12:13], v[16:17] op_sel:[1,0] op_sel_hi:[0,1]
	v_mov_b32_e32 v15, v12
	v_pk_add_f32 v[18:19], v[14:15], v[20:21] neg_lo:[0,1] neg_hi:[0,1]
	v_mov_b32_e32 v9, v16
	v_sub_f32_e32 v7, v14, v18
	v_pk_add_f32 v[8:9], v[8:9], v[18:19] neg_lo:[0,1] neg_hi:[0,1]
	v_sub_f32_e32 v7, v20, v7
	v_add_f32_e32 v7, v8, v7
	v_add_f32_e32 v7, v7, v9
	v_add_f32_e32 v7, v12, v7
	v_cndmask_b32_e32 v7, v59, v7, vcc
	v_cmp_lt_f32_e64 vcc, |v1|, s45
	s_nop 1
	v_cndmask_b32_e32 v7, v7, v1, vcc
; __device__ __forceinline__ float softplus_(float x) { return x > 20.f ? x : log1pf(expf(x)); }
; template <int ph>
; __device__ __forceinline__ void run_phase(const Args& args, LAS unsigned char* lds, const int G, const int bx, const bool fin = true) {
;     ...
;                 const f32x4 lam0 = *(const f32x4*)(lru_lambda + ch), lam1 = *(const f32x4*)(lru_lambda + ch + 4);
;                 const f32x4 sp0 = (f32x4){softplus_(-lam0[0]), softplus_(-lam0[1]), softplus_(-lam0[2]), softplus_(-lam0[3])} * -8.0f,
;                             sp1 = (f32x4){softplus_(-lam1[0]), softplus_(-lam1[1]), softplus_(-lam1[2]), softplus_(-lam1[3])} * -8.0f;
.LBB0_1052:
	s_or_b64 exec, exec, s[0:1]
	s_waitcnt vmcnt(0)
	v_xor_b32_e32 v8, 0x80000000, v2
	v_cmp_ngt_f32_e32 vcc, s38, v2
	s_and_saveexec_b64 s[0:1], vcc
	s_cbranch_execz .LBB0_1054
	v_mul_f32_e32 v1, 0xbfb8aa3b, v2
	v_rndne_f32_e32 v8, v1
	v_sub_f32_e32 v9, v1, v8
	v_fma_f32 v1, v2, s39, -v1
	v_fmac_f32_e32 v1, 0xb2a5705f, v2
	v_add_f32_e32 v1, v9, v1
	v_cvt_i32_f32_e32 v8, v8
	v_exp_f32_e32 v1, v1
	v_cmp_nlt_f32_e32 vcc, s40, v2
	v_ldexp_f32 v1, v1, v8
	s_nop 0
	v_cndmask_b32_e32 v1, 0, v1, vcc
	v_cmp_ngt_f32_e32 vcc, s41, v2
	s_nop 1
	v_cndmask_b32_e32 v1, v59, v1, vcc
	v_add_f32_e32 v2, 1.0, v1
	v_add_f32_e32 v8, -1.0, v2
	v_sub_f32_e32 v9, v8, v2
	v_add_f32_e32 v9, 1.0, v9
	v_sub_f32_e32 v8, v1, v8
	v_add_f32_e32 v12, v8, v9
	v_frexp_mant_f32_e32 v13, v2
	v_cvt_f64_f32_e32 v[8:9], v2
	v_frexp_exp_i32_f64_e32 v8, v[8:9]
	v_cmp_gt_f32_e32 vcc, s43, v13
	s_nop 1
	v_subbrev_co_u32_e32 v18, vcc, 0, v8, vcc
	v_sub_u32_e32 v8, 0, v18
	v_ldexp_f32 v2, v2, v8
	v_ldexp_f32 v8, v12, v8
	v_add_f32_e32 v12, -1.0, v2
	v_add_f32_e32 v9, 1.0, v12
	v_sub_f32_e32 v9, v2, v9
	v_add_f32_e32 v13, v8, v9
	v_add_f32_e32 v9, 1.0, v2
	v_add_f32_e32 v14, -1.0, v9
	v_sub_f32_e32 v2, v2, v14
	v_add_f32_e32 v2, v8, v2
	v_add_f32_e32 v19, v9, v2
	s_nop 0
	v_rcp_f32_e32 v20, v19
	v_sub_f32_e32 v8, v9, v19
	v_add_f32_e32 v9, v12, v13
	v_add_f32_e32 v2, v2, v8
	v_mul_f32_e32 v25, v9, v20
	v_sub_f32_e32 v8, v12, v9
	v_mul_f32_e32 v12, v19, v25
	v_fma_f32 v14, v25, v19, -v12
	v_fmac_f32_e32 v14, v25, v2
	v_add_f32_e32 v21, v13, v8
	v_add_f32_e32 v8, v12, v14
	v_sub_f32_e32 v13, v9, v8
	v_pk_add_f32 v[16:17], v[8:9], v[12:13] neg_lo:[0,1] neg_hi:[0,1]
	v_mov_b32_e32 v15, v8
	v_pk_add_f32 v[8:9], v[16:17], v[14:15] neg_lo:[0,1] neg_hi:[0,1]
	v_cmp_neq_f32_e32 vcc, s42, v1
	v_add_f32_e32 v9, v21, v9
	v_add_f32_e32 v8, v8, v9
	v_add_f32_e32 v9, v13, v8
	v_mul_f32_e32 v21, v20, v9
	v_mul_f32_e32 v12, v19, v21
	v_fma_f32 v14, v21, v19, -v12
	v_fmac_f32_e32 v14, v21, v2
	v_sub_f32_e32 v2, v13, v9
	v_add_f32_e32 v2, v8, v2
	v_add_f32_e32 v8, v12, v14
	v_sub_f32_e32 v13, v9, v8
	v_pk_add_f32 v[16:17], v[8:9], v[12:13] neg_lo:[0,1] neg_hi:[0,1]
	v_mov_b32_e32 v15, v8
	v_pk_add_f32 v[8:9], v[16:17], v[14:15] neg_lo:[0,1] neg_hi:[0,1]
	s_nop 0
	v_add_f32_e32 v2, v2, v9
	v_add_f32_e32 v2, v8, v2
	v_add_f32_e32 v9, v25, v21
	v_add_f32_e32 v2, v13, v2
	v_sub_f32_e32 v8, v9, v25
	v_mul_f32_e32 v2, v20, v2
	v_sub_f32_e32 v8, v21, v8
	v_add_f32_e32 v2, v8, v2
	v_add_f32_e32 v12, v9, v2
	v_mul_f32_e32 v14, v12, v12
	v_fmamk_f32 v8, v14, 0x3e9b6dac, v57
	v_fmaak_f32 v25, v14, v8, 0x3f2aaada
	v_cvt_f32_i32_e32 v8, v18
	v_sub_f32_e32 v9, v12, v9
	v_sub_f32_e32 v2, v2, v9
	v_mul_f32_e32 v9, v12, v14
	v_pk_mul_f32 v[14:15], v[8:9], v[24:25]
	v_ldexp_f32 v13, v12, 1
	v_fma_f32 v12, v8, s44, -v14
	v_fmac_f32_e32 v12, 0xb102e308, v8
	v_pk_add_f32 v[8:9], v[14:15], v[12:13]
	v_ldexp_f32 v2, v2, 1
	v_sub_f32_e32 v13, v9, v13
	v_sub_f32_e32 v13, v15, v13
	v_add_f32_e32 v17, v2, v13
	v_mov_b32_e32 v16, v14
	v_pk_add_f32 v[14:15], v[8:9], v[14:15] neg_lo:[0,1] neg_hi:[0,1]
	v_pk_add_f32 v[18:19], v[8:9], v[16:17]
	v_mov_b32_e32 v13, v8
	v_mov_b32_e32 v15, v19
	v_pk_add_f32 v[20:21], v[12:13], v[14:15] neg_lo:[0,1] neg_hi:[0,1]
	v_pk_add_f32 v[12:13], v[12:13], v[14:15]
	v_mov_b32_e32 v16, v17
	v_pk_add_f32 v[14:15], v[12:13], v[8:9] op_sel:[1,0] op_sel_hi:[0,1] neg_lo:[0,1] neg_hi:[0,1]
	v_pk_add_f32 v[26:27], v[18:19], v[14:15] op_sel_hi:[1,0] neg_lo:[0,1] neg_hi:[0,1]
	v_mov_b32_e32 v18, v19
	v_mov_b32_e32 v19, v13
	v_pk_mov_b32 v[14:15], v[8:9], v[14:15] op_sel:[1,0]
	v_mov_b32_e32 v17, v8
	v_pk_add_f32 v[14:15], v[18:19], v[14:15] neg_lo:[0,1] neg_hi:[0,1]
	v_mov_b32_e32 v26, v20
	v_pk_add_f32 v[8:9], v[16:17], v[14:15] neg_lo:[0,1] neg_hi:[0,1]
	v_mov_b32_e32 v21, v13
	v_pk_add_f32 v[14:15], v[26:27], v[8:9]
	s_nop 0
	v_pk_add_f32 v[16:17], v[14:15], v[14:15] op_sel:[0,1] op_sel_hi:[1,0]
	s_nop 0
	v_pk_add_f32 v[12:13], v[12:13], v[16:17] op_sel:[1,0] op_sel_hi:[0,1]
	v_mov_b32_e32 v15, v12
	v_pk_add_f32 v[18:19], v[14:15], v[20:21] neg_lo:[0,1] neg_hi:[0,1]
	v_mov_b32_e32 v9, v16
	v_sub_f32_e32 v2, v14, v18
	v_pk_add_f32 v[8:9], v[8:9], v[18:19] neg_lo:[0,1] neg_hi:[0,1]
	v_sub_f32_e32 v2, v20, v2
	v_add_f32_e32 v2, v8, v2
	v_add_f32_e32 v2, v2, v9
	v_add_f32_e32 v2, v12, v2
	v_cndmask_b32_e32 v2, v59, v2, vcc
	v_cmp_lt_f32_e64 vcc, |v1|, s45
	s_nop 1
	v_cndmask_b32_e32 v8, v2, v1, vcc
; __device__ __forceinline__ float softplus_(float x) { return x > 20.f ? x : log1pf(expf(x)); }
; template <int ph>
; __device__ __forceinline__ void run_phase(const Args& args, LAS unsigned char* lds, const int G, const int bx, const bool fin = true) {
;     ...
;                 const f32x4 lam0 = *(const f32x4*)(lru_lambda + ch), lam1 = *(const f32x4*)(lru_lambda + ch + 4);
;                 const f32x4 sp0 = (f32x4){softplus_(-lam0[0]), softplus_(-lam0[1]), softplus_(-lam0[2]), softplus_(-lam0[3])} * -8.0f,
;                             sp1 = (f32x4){softplus_(-lam1[0]), softplus_(-lam1[1]), softplus_(-lam1[2]), softplus_(-lam1[3])} * -8.0f;
.LBB0_1054:
	s_or_b64 exec, exec, s[0:1]
	v_xor_b32_e32 v9, 0x80000000, v3
	v_cmp_ngt_f32_e32 vcc, s38, v3
	s_and_saveexec_b64 s[0:1], vcc
	s_cbranch_execz .LBB0_1056
	v_mul_f32_e32 v1, 0xbfb8aa3b, v3
	v_rndne_f32_e32 v2, v1
	v_sub_f32_e32 v9, v1, v2
	v_fma_f32 v1, v3, s39, -v1
	v_fmac_f32_e32 v1, 0xb2a5705f, v3
	v_add_f32_e32 v1, v9, v1
	v_cvt_i32_f32_e32 v2, v2
	v_exp_f32_e32 v1, v1
	v_cmp_nlt_f32_e32 vcc, s40, v3
	v_ldexp_f32 v1, v1, v2
	s_nop 0
	v_cndmask_b32_e32 v1, 0, v1, vcc
	v_cmp_ngt_f32_e32 vcc, s41, v3
	s_nop 1
	v_cndmask_b32_e32 v1, v59, v1, vcc
	v_add_f32_e32 v9, 1.0, v1
	v_add_f32_e32 v2, -1.0, v9
	v_sub_f32_e32 v3, v2, v9
	v_add_f32_e32 v3, 1.0, v3
	v_sub_f32_e32 v2, v1, v2
	v_add_f32_e32 v12, v2, v3
	v_frexp_mant_f32_e32 v13, v9
	v_cvt_f64_f32_e32 v[2:3], v9
	v_frexp_exp_i32_f64_e32 v2, v[2:3]
	v_cmp_gt_f32_e32 vcc, s43, v13
	s_nop 1
	v_subbrev_co_u32_e32 v18, vcc, 0, v2, vcc
	v_sub_u32_e32 v2, 0, v18
	v_ldexp_f32 v3, v9, v2
	v_add_f32_e32 v9, -1.0, v3
	v_add_f32_e32 v13, 1.0, v3
	v_ldexp_f32 v2, v12, v2
	v_add_f32_e32 v12, 1.0, v9
	v_add_f32_e32 v14, -1.0, v13
	v_sub_f32_e32 v12, v3, v12
	v_sub_f32_e32 v3, v3, v14
	v_add_f32_e32 v12, v2, v12
	v_add_f32_e32 v2, v2, v3
	v_add_f32_e32 v19, v13, v2
	s_nop 0
	v_rcp_f32_e32 v21, v19
	v_sub_f32_e32 v3, v13, v19
	v_add_f32_e32 v20, v2, v3
	v_add_f32_e32 v3, v9, v12
	v_sub_f32_e32 v2, v9, v3
	v_mul_f32_e32 v25, v3, v21
	v_add_f32_e32 v9, v12, v2
	v_mul_f32_e32 v12, v19, v25
	v_fma_f32 v14, v25, v19, -v12
	v_fmac_f32_e32 v14, v25, v20
	v_add_f32_e32 v2, v12, v14
	v_sub_f32_e32 v13, v3, v2
	v_pk_add_f32 v[16:17], v[2:3], v[12:13] neg_lo:[0,1] neg_hi:[0,1]
	v_mov_b32_e32 v15, v2
	v_pk_add_f32 v[2:3], v[16:17], v[14:15] neg_lo:[0,1] neg_hi:[0,1]
	v_cmp_neq_f32_e32 vcc, s42, v1
	v_add_f32_e32 v3, v9, v3
	v_add_f32_e32 v2, v2, v3
	v_add_f32_e32 v3, v13, v2
	v_mul_f32_e32 v9, v21, v3
	v_mul_f32_e32 v12, v19, v9
	v_fma_f32 v14, v9, v19, -v12
	v_fmac_f32_e32 v14, v9, v20
	v_sub_f32_e32 v13, v13, v3
	v_add_f32_e32 v19, v2, v13
	v_add_f32_e32 v2, v12, v14
	v_sub_f32_e32 v13, v3, v2
	v_pk_add_f32 v[16:17], v[2:3], v[12:13] neg_lo:[0,1] neg_hi:[0,1]
	v_mov_b32_e32 v15, v2
	v_pk_add_f32 v[2:3], v[16:17], v[14:15] neg_lo:[0,1] neg_hi:[0,1]
	s_nop 0
	v_add_f32_e32 v3, v19, v3
	v_add_f32_e32 v2, v2, v3
	v_add_f32_e32 v3, v25, v9
	v_add_f32_e32 v2, v13, v2
	v_sub_f32_e32 v12, v3, v25
	v_mul_f32_e32 v2, v21, v2
	v_sub_f32_e32 v9, v9, v12
	v_add_f32_e32 v9, v9, v2
	v_add_f32_e32 v12, v3, v9
	v_mul_f32_e32 v14, v12, v12
	v_fmamk_f32 v2, v14, 0x3e9b6dac, v57
	v_fmaak_f32 v25, v14, v2, 0x3f2aaada
	v_cvt_f32_i32_e32 v2, v18
	v_sub_f32_e32 v3, v12, v3
	v_sub_f32_e32 v3, v9, v3
	v_ldexp_f32 v9, v3, 1
	v_mul_f32_e32 v3, v12, v14
	v_pk_mul_f32 v[14:15], v[2:3], v[24:25]
	v_ldexp_f32 v13, v12, 1
	v_fma_f32 v12, v2, s44, -v14
	v_fmac_f32_e32 v12, 0xb102e308, v2
	v_pk_add_f32 v[2:3], v[14:15], v[12:13]
	v_mov_b32_e32 v16, v14
	v_sub_f32_e32 v13, v3, v13
	v_sub_f32_e32 v13, v15, v13
	v_add_f32_e32 v17, v9, v13
	v_pk_add_f32 v[14:15], v[2:3], v[14:15] neg_lo:[0,1] neg_hi:[0,1]
	v_pk_add_f32 v[18:19], v[2:3], v[16:17]
	v_mov_b32_e32 v13, v2
	v_mov_b32_e32 v15, v19
	v_pk_add_f32 v[20:21], v[12:13], v[14:15] neg_lo:[0,1] neg_hi:[0,1]
	v_pk_add_f32 v[12:13], v[12:13], v[14:15]
	v_mov_b32_e32 v16, v17
	v_pk_add_f32 v[14:15], v[12:13], v[2:3] op_sel:[1,0] op_sel_hi:[0,1] neg_lo:[0,1] neg_hi:[0,1]
	v_pk_add_f32 v[26:27], v[18:19], v[14:15] op_sel_hi:[1,0] neg_lo:[0,1] neg_hi:[0,1]
	v_mov_b32_e32 v18, v19
	v_mov_b32_e32 v19, v13
	v_pk_mov_b32 v[14:15], v[2:3], v[14:15] op_sel:[1,0]
	v_mov_b32_e32 v17, v2
	v_pk_add_f32 v[14:15], v[18:19], v[14:15] neg_lo:[0,1] neg_hi:[0,1]
	v_mov_b32_e32 v26, v20
	v_pk_add_f32 v[2:3], v[16:17], v[14:15] neg_lo:[0,1] neg_hi:[0,1]
	v_mov_b32_e32 v21, v13
	v_pk_add_f32 v[14:15], v[26:27], v[2:3]
	s_nop 0
	v_pk_add_f32 v[16:17], v[14:15], v[14:15] op_sel:[0,1] op_sel_hi:[1,0]
	s_nop 0
	v_pk_add_f32 v[12:13], v[12:13], v[16:17] op_sel:[1,0] op_sel_hi:[0,1]
	v_mov_b32_e32 v15, v12
	v_pk_add_f32 v[18:19], v[14:15], v[20:21] neg_lo:[0,1] neg_hi:[0,1]
	v_mov_b32_e32 v3, v16
	v_sub_f32_e32 v9, v14, v18
	v_pk_add_f32 v[2:3], v[2:3], v[18:19] neg_lo:[0,1] neg_hi:[0,1]
	v_sub_f32_e32 v9, v20, v9
	v_add_f32_e32 v2, v2, v9
	v_add_f32_e32 v2, v2, v3
	v_add_f32_e32 v2, v12, v2
	v_cndmask_b32_e32 v2, v59, v2, vcc
	v_cmp_lt_f32_e64 vcc, |v1|, s45
	s_nop 1
	v_cndmask_b32_e32 v9, v2, v1, vcc
; __device__ __forceinline__ float softplus_(float x) { return x > 20.f ? x : log1pf(expf(x)); }
; template <int ph>
; __device__ __forceinline__ void run_phase(const Args& args, LAS unsigned char* lds, const int G, const int bx, const bool fin = true) {
;     ...
;                 const f32x4 lam0 = *(const f32x4*)(lru_lambda + ch), lam1 = *(const f32x4*)(lru_lambda + ch + 4);
;                 const f32x4 sp0 = (f32x4){softplus_(-lam0[0]), softplus_(-lam0[1]), softplus_(-lam0[2]), softplus_(-lam0[3])} * -8.0f,
;                             sp1 = (f32x4){softplus_(-lam1[0]), softplus_(-lam1[1]), softplus_(-lam1[2]), softplus_(-lam1[3])} * -8.0f;
.LBB0_1056:
	s_or_b64 exec, exec, s[0:1]
	v_xor_b32_e32 v2, 0x80000000, v4
	v_cmp_ngt_f32_e32 vcc, s38, v4
	s_and_saveexec_b64 s[0:1], vcc
	s_cbranch_execz .LBB0_1058
	v_mul_f32_e32 v1, 0xbfb8aa3b, v4
	v_rndne_f32_e32 v2, v1
	v_sub_f32_e32 v3, v1, v2
	v_fma_f32 v1, v4, s39, -v1
	v_fmac_f32_e32 v1, 0xb2a5705f, v4
	v_add_f32_e32 v1, v3, v1
	v_cvt_i32_f32_e32 v2, v2
	v_exp_f32_e32 v1, v1
	v_cmp_nlt_f32_e32 vcc, s40, v4
	v_ldexp_f32 v1, v1, v2
	s_nop 0
	v_cndmask_b32_e32 v1, 0, v1, vcc
	v_cmp_ngt_f32_e32 vcc, s41, v4
	s_nop 1
	v_cndmask_b32_e32 v1, v59, v1, vcc
	v_add_f32_e32 v4, 1.0, v1
	v_add_f32_e32 v2, -1.0, v4
	v_sub_f32_e32 v3, v2, v4
	v_add_f32_e32 v3, 1.0, v3
	v_sub_f32_e32 v2, v1, v2
	v_add_f32_e32 v12, v2, v3
	v_frexp_mant_f32_e32 v13, v4
	v_cvt_f64_f32_e32 v[2:3], v4
	v_frexp_exp_i32_f64_e32 v2, v[2:3]
	v_cmp_gt_f32_e32 vcc, s43, v13
	s_nop 1
	v_subbrev_co_u32_e32 v18, vcc, 0, v2, vcc
	v_sub_u32_e32 v2, 0, v18
	v_ldexp_f32 v3, v4, v2
	v_add_f32_e32 v4, -1.0, v3
	v_add_f32_e32 v13, 1.0, v3
	v_ldexp_f32 v2, v12, v2
	v_add_f32_e32 v12, 1.0, v4
	v_add_f32_e32 v14, -1.0, v13
	v_sub_f32_e32 v12, v3, v12
	v_sub_f32_e32 v3, v3, v14
	v_add_f32_e32 v12, v2, v12
	v_add_f32_e32 v2, v2, v3
	v_add_f32_e32 v19, v13, v2
	s_nop 0
	v_rcp_f32_e32 v21, v19
	v_sub_f32_e32 v3, v13, v19
	v_add_f32_e32 v20, v2, v3
	v_add_f32_e32 v3, v4, v12
	v_sub_f32_e32 v2, v4, v3
	v_mul_f32_e32 v25, v3, v21
	v_add_f32_e32 v4, v12, v2
	v_mul_f32_e32 v12, v19, v25
	v_fma_f32 v14, v25, v19, -v12
	v_fmac_f32_e32 v14, v25, v20
	v_add_f32_e32 v2, v12, v14
	v_sub_f32_e32 v13, v3, v2
	v_pk_add_f32 v[16:17], v[2:3], v[12:13] neg_lo:[0,1] neg_hi:[0,1]
	v_mov_b32_e32 v15, v2
	v_pk_add_f32 v[2:3], v[16:17], v[14:15] neg_lo:[0,1] neg_hi:[0,1]
	v_cmp_neq_f32_e32 vcc, s42, v1
	v_add_f32_e32 v3, v4, v3
	v_add_f32_e32 v2, v2, v3
	v_add_f32_e32 v3, v13, v2
	v_mul_f32_e32 v4, v21, v3
	v_mul_f32_e32 v12, v19, v4
	v_fma_f32 v14, v4, v19, -v12
	v_fmac_f32_e32 v14, v4, v20
	v_sub_f32_e32 v13, v13, v3
	v_add_f32_e32 v19, v2, v13
	v_add_f32_e32 v2, v12, v14
	v_sub_f32_e32 v13, v3, v2
	v_pk_add_f32 v[16:17], v[2:3], v[12:13] neg_lo:[0,1] neg_hi:[0,1]
	v_mov_b32_e32 v15, v2
	v_pk_add_f32 v[2:3], v[16:17], v[14:15] neg_lo:[0,1] neg_hi:[0,1]
	s_nop 0
	v_add_f32_e32 v3, v19, v3
	v_add_f32_e32 v2, v2, v3
	v_add_f32_e32 v3, v25, v4
	v_add_f32_e32 v2, v13, v2
	v_sub_f32_e32 v12, v3, v25
	v_mul_f32_e32 v2, v21, v2
	v_sub_f32_e32 v4, v4, v12
	v_add_f32_e32 v4, v4, v2
	v_add_f32_e32 v12, v3, v4
	v_mul_f32_e32 v14, v12, v12
	v_fmamk_f32 v2, v14, 0x3e9b6dac, v57
	v_fmaak_f32 v25, v14, v2, 0x3f2aaada
	v_cvt_f32_i32_e32 v2, v18
	v_sub_f32_e32 v3, v12, v3
	v_sub_f32_e32 v3, v4, v3
	v_ldexp_f32 v4, v3, 1
	v_mul_f32_e32 v3, v12, v14
	v_pk_mul_f32 v[14:15], v[2:3], v[24:25]
	v_ldexp_f32 v13, v12, 1
	v_fma_f32 v12, v2, s44, -v14
	v_fmac_f32_e32 v12, 0xb102e308, v2
	v_pk_add_f32 v[2:3], v[14:15], v[12:13]
	v_mov_b32_e32 v16, v14
	v_sub_f32_e32 v13, v3, v13
	v_sub_f32_e32 v13, v15, v13
	v_add_f32_e32 v17, v4, v13
	v_pk_add_f32 v[14:15], v[2:3], v[14:15] neg_lo:[0,1] neg_hi:[0,1]
	v_pk_add_f32 v[18:19], v[2:3], v[16:17]
	v_mov_b32_e32 v13, v2
	v_mov_b32_e32 v15, v19
	v_pk_add_f32 v[20:21], v[12:13], v[14:15] neg_lo:[0,1] neg_hi:[0,1]
	v_pk_add_f32 v[12:13], v[12:13], v[14:15]
	v_mov_b32_e32 v16, v17
	v_pk_add_f32 v[14:15], v[12:13], v[2:3] op_sel:[1,0] op_sel_hi:[0,1] neg_lo:[0,1] neg_hi:[0,1]
	v_pk_add_f32 v[26:27], v[18:19], v[14:15] op_sel_hi:[1,0] neg_lo:[0,1] neg_hi:[0,1]
	v_mov_b32_e32 v18, v19
	v_mov_b32_e32 v19, v13
	v_pk_mov_b32 v[14:15], v[2:3], v[14:15] op_sel:[1,0]
	v_mov_b32_e32 v17, v2
	v_pk_add_f32 v[14:15], v[18:19], v[14:15] neg_lo:[0,1] neg_hi:[0,1]
	v_mov_b32_e32 v26, v20
	v_pk_add_f32 v[2:3], v[16:17], v[14:15] neg_lo:[0,1] neg_hi:[0,1]
	v_mov_b32_e32 v21, v13
	v_pk_add_f32 v[14:15], v[26:27], v[2:3]
	s_nop 0
	v_pk_add_f32 v[16:17], v[14:15], v[14:15] op_sel:[0,1] op_sel_hi:[1,0]
	s_nop 0
	v_pk_add_f32 v[12:13], v[12:13], v[16:17] op_sel:[1,0] op_sel_hi:[0,1]
	v_mov_b32_e32 v15, v12
	v_pk_add_f32 v[18:19], v[14:15], v[20:21] neg_lo:[0,1] neg_hi:[0,1]
	v_mov_b32_e32 v3, v16
	v_sub_f32_e32 v4, v14, v18
	v_pk_add_f32 v[2:3], v[2:3], v[18:19] neg_lo:[0,1] neg_hi:[0,1]
	v_sub_f32_e32 v4, v20, v4
	v_add_f32_e32 v2, v2, v4
	v_add_f32_e32 v2, v2, v3
	v_add_f32_e32 v2, v12, v2
	v_cndmask_b32_e32 v2, v59, v2, vcc
	v_cmp_lt_f32_e64 vcc, |v1|, s45
	s_nop 1
	v_cndmask_b32_e32 v2, v2, v1, vcc
; __device__ __forceinline__ float softplus_(float x) { return x > 20.f ? x : log1pf(expf(x)); }
; template <int ph>
; __device__ __forceinline__ void run_phase(const Args& args, LAS unsigned char* lds, const int G, const int bx, const bool fin = true) {
;     ...
;                 const f32x4 lam0 = *(const f32x4*)(lru_lambda + ch), lam1 = *(const f32x4*)(lru_lambda + ch + 4);
;                 const f32x4 sp0 = (f32x4){softplus_(-lam0[0]), softplus_(-lam0[1]), softplus_(-lam0[2]), softplus_(-lam0[3])} * -8.0f,
;                             sp1 = (f32x4){softplus_(-lam1[0]), softplus_(-lam1[1]), softplus_(-lam1[2]), softplus_(-lam1[3])} * -8.0f;
.LBB0_1058:
	s_or_b64 exec, exec, s[0:1]
	v_xor_b32_e32 v3, 0x80000000, v5
	v_cmp_ngt_f32_e32 vcc, s38, v5
	s_and_saveexec_b64 s[0:1], vcc
	s_cbranch_execz .LBB0_1060
	v_mul_f32_e32 v1, 0xbfb8aa3b, v5
	v_rndne_f32_e32 v3, v1
	v_sub_f32_e32 v4, v1, v3
	v_fma_f32 v1, v5, s39, -v1
	v_fmac_f32_e32 v1, 0xb2a5705f, v5
	v_add_f32_e32 v1, v4, v1
	v_cvt_i32_f32_e32 v3, v3
	v_exp_f32_e32 v1, v1
	v_cmp_nlt_f32_e32 vcc, s40, v5
	v_ldexp_f32 v1, v1, v3
	s_nop 0
	v_cndmask_b32_e32 v1, 0, v1, vcc
	v_cmp_ngt_f32_e32 vcc, s41, v5
	s_nop 1
	v_cndmask_b32_e32 v1, v59, v1, vcc
	v_add_f32_e32 v3, 1.0, v1
	v_add_f32_e32 v4, -1.0, v3
	v_sub_f32_e32 v5, v4, v3
	v_add_f32_e32 v5, 1.0, v5
	v_sub_f32_e32 v4, v1, v4
	v_add_f32_e32 v12, v4, v5
	v_frexp_mant_f32_e32 v13, v3
	v_cvt_f64_f32_e32 v[4:5], v3
	v_frexp_exp_i32_f64_e32 v4, v[4:5]
	v_cmp_gt_f32_e32 vcc, s43, v13
	s_nop 1
	v_subbrev_co_u32_e32 v18, vcc, 0, v4, vcc
	v_sub_u32_e32 v4, 0, v18
	v_ldexp_f32 v3, v3, v4
	v_ldexp_f32 v4, v12, v4
	v_add_f32_e32 v12, -1.0, v3
	v_add_f32_e32 v5, 1.0, v12
	v_sub_f32_e32 v5, v3, v5
	v_add_f32_e32 v13, v4, v5
	v_add_f32_e32 v5, 1.0, v3
	v_add_f32_e32 v14, -1.0, v5
	v_sub_f32_e32 v3, v3, v14
	v_add_f32_e32 v3, v4, v3
	v_add_f32_e32 v19, v5, v3
	s_nop 0
	v_rcp_f32_e32 v20, v19
	v_sub_f32_e32 v4, v5, v19
	v_add_f32_e32 v5, v12, v13
	v_add_f32_e32 v3, v3, v4
	v_mul_f32_e32 v25, v5, v20
	v_sub_f32_e32 v4, v12, v5
	v_mul_f32_e32 v12, v19, v25
	v_fma_f32 v14, v25, v19, -v12
	v_fmac_f32_e32 v14, v25, v3
	v_add_f32_e32 v21, v13, v4
	v_add_f32_e32 v4, v12, v14
	v_sub_f32_e32 v13, v5, v4
	v_pk_add_f32 v[16:17], v[4:5], v[12:13] neg_lo:[0,1] neg_hi:[0,1]
	v_mov_b32_e32 v15, v4
	v_pk_add_f32 v[4:5], v[16:17], v[14:15] neg_lo:[0,1] neg_hi:[0,1]
	v_cmp_neq_f32_e32 vcc, s42, v1
	v_add_f32_e32 v5, v21, v5
	v_add_f32_e32 v4, v4, v5
	v_add_f32_e32 v5, v13, v4
	v_mul_f32_e32 v21, v20, v5
	v_mul_f32_e32 v12, v19, v21
	v_fma_f32 v14, v21, v19, -v12
	v_fmac_f32_e32 v14, v21, v3
	v_sub_f32_e32 v3, v13, v5
	v_add_f32_e32 v3, v4, v3
	v_add_f32_e32 v4, v12, v14
	v_sub_f32_e32 v13, v5, v4
	v_pk_add_f32 v[16:17], v[4:5], v[12:13] neg_lo:[0,1] neg_hi:[0,1]
	v_mov_b32_e32 v15, v4
	v_pk_add_f32 v[4:5], v[16:17], v[14:15] neg_lo:[0,1] neg_hi:[0,1]
	s_nop 0
	v_add_f32_e32 v3, v3, v5
	v_add_f32_e32 v3, v4, v3
	v_add_f32_e32 v5, v25, v21
	v_add_f32_e32 v3, v13, v3
	v_sub_f32_e32 v4, v5, v25
	v_mul_f32_e32 v3, v20, v3
	v_sub_f32_e32 v4, v21, v4
	v_add_f32_e32 v3, v4, v3
	v_add_f32_e32 v12, v5, v3
	v_mul_f32_e32 v14, v12, v12
	v_fmamk_f32 v4, v14, 0x3e9b6dac, v57
	v_fmaak_f32 v25, v14, v4, 0x3f2aaada
	v_cvt_f32_i32_e32 v4, v18
	v_sub_f32_e32 v5, v12, v5
	v_sub_f32_e32 v3, v3, v5
	v_mul_f32_e32 v5, v12, v14
	v_pk_mul_f32 v[14:15], v[4:5], v[24:25]
	v_ldexp_f32 v13, v12, 1
	v_fma_f32 v12, v4, s44, -v14
	v_fmac_f32_e32 v12, 0xb102e308, v4
	v_pk_add_f32 v[4:5], v[14:15], v[12:13]
	v_ldexp_f32 v3, v3, 1
	v_sub_f32_e32 v13, v5, v13
	v_sub_f32_e32 v13, v15, v13
	v_add_f32_e32 v17, v3, v13
	v_mov_b32_e32 v16, v14
	v_pk_add_f32 v[14:15], v[4:5], v[14:15] neg_lo:[0,1] neg_hi:[0,1]
	v_pk_add_f32 v[18:19], v[4:5], v[16:17]
	v_mov_b32_e32 v13, v4
	v_mov_b32_e32 v15, v19
	v_pk_add_f32 v[20:21], v[12:13], v[14:15] neg_lo:[0,1] neg_hi:[0,1]
	v_pk_add_f32 v[12:13], v[12:13], v[14:15]
	v_mov_b32_e32 v16, v17
	v_pk_add_f32 v[14:15], v[12:13], v[4:5] op_sel:[1,0] op_sel_hi:[0,1] neg_lo:[0,1] neg_hi:[0,1]
	v_pk_add_f32 v[26:27], v[18:19], v[14:15] op_sel_hi:[1,0] neg_lo:[0,1] neg_hi:[0,1]
	v_mov_b32_e32 v18, v19
	v_mov_b32_e32 v19, v13
	v_pk_mov_b32 v[14:15], v[4:5], v[14:15] op_sel:[1,0]
	v_mov_b32_e32 v17, v4
	v_pk_add_f32 v[14:15], v[18:19], v[14:15] neg_lo:[0,1] neg_hi:[0,1]
	v_mov_b32_e32 v26, v20
	v_pk_add_f32 v[4:5], v[16:17], v[14:15] neg_lo:[0,1] neg_hi:[0,1]
	v_mov_b32_e32 v21, v13
	v_pk_add_f32 v[14:15], v[26:27], v[4:5]
	s_nop 0
	v_pk_add_f32 v[16:17], v[14:15], v[14:15] op_sel:[0,1] op_sel_hi:[1,0]
	s_nop 0
	v_pk_add_f32 v[12:13], v[12:13], v[16:17] op_sel:[1,0] op_sel_hi:[0,1]
	v_mov_b32_e32 v15, v12
	v_pk_add_f32 v[18:19], v[14:15], v[20:21] neg_lo:[0,1] neg_hi:[0,1]
	v_mov_b32_e32 v5, v16
	v_sub_f32_e32 v3, v14, v18
	v_pk_add_f32 v[4:5], v[4:5], v[18:19] neg_lo:[0,1] neg_hi:[0,1]
	v_sub_f32_e32 v3, v20, v3
	v_add_f32_e32 v3, v4, v3
	v_add_f32_e32 v3, v3, v5
	v_add_f32_e32 v3, v12, v3
	v_cndmask_b32_e32 v3, v59, v3, vcc
	v_cmp_lt_f32_e64 vcc, |v1|, s45
	s_nop 1
	v_cndmask_b32_e32 v3, v3, v1, vcc
